# attention task loop: K/V row gathers addressed as SGPR base + 32-bit VGPR offset (1 VALU per gather instead of 4; -341 instructions per task)
# speedup vs baseline: 1.0204x; 1.0027x over previous
; __device__ __forceinline__ int lane_opaque() { int l; asm volatile("v_mbcnt_lo_u32_b32 %0, -1, 0\n\tv_mbcnt_hi_u32_b32 %0, -1, %0" : "=v"(l)); return l; }
; #define LAS __attribute__((address_space(3)))
; DI void attn_worker(unsigned char* ws, LAS unsigned char* lds, LAS unsigned* qctr, int wave) {
;     const int lane = lane_opaque();
;     const bf16* q = (const bf16*)(ws + WS_Q); const bf16* kbuf = (const bf16*)(ws + WS_K); const bf16* vbuf = (const bf16*)(ws + WS_V);
;     const int* idx = (const int*)(ws + WS_IDX); bf16* ao = (bf16*)(ws + WS_AO);
;     LAS int* idl = (LAS int*)(lds); LAS int* idl2 = (LAS int*)(lds + 1024); LAS float* pl = (LAS float*)(lds + 2048);
;     LAS unsigned char* stg = lds + 6144;
;     const int G = gridDim.x, bg = blockIdx.x & 7, b = bg >> 2, g = bg & 3;
;     unsigned* gq = (unsigned*)(ws + WS_CTL) + CW_ATTQ + 64 * bg;
;     (void)G;
;     const int kr = lane & 15, kq = lane >> 4;
;     const int kg = lane >> 4, dg = lane & 15;
;     const int rg = lane >> 4, cc = lane & 15;
;     const bf16* kvb = kbuf + (size_t)(b * SEQ) * KVD + g * 128 + 8 * cc;
;     int woff[4], roff[4];
; #pragma unroll
;     for (int i = 0; i < 4; ++i) { const int row = 4 * i + rg; woff[i] = row * 256 + ((cc ^ row) & 15) * 16; roff[i] = cc * 256 + (((4 * i + rg) ^ cc) & 15) * 16; }
;     unsigned vwb[2], vtb[2][2];
;     { const int q4 = (lane & 15) >> 2, p4 = lane & 3;
; #pragma unroll
;       for (int h2 = 0; h2 < 2; ++h2) { vwb[h2] = (unsigned)(size_t)stg + 2048 * rg + 512 * (cc >> 2) + 16 * ((cc & 3) ^ ((2 * rg + h2) & 3));
; #pragma unroll
;         for (int par = 0; par < 2; ++par) vtb[h2][par] = (unsigned)(size_t)stg + 2048 * rg + 64 * (4 * h2 + q4) + 16 * ((2 * par + (p4 >> 1)) ^ ((2 * rg + h2) & 3)) + 8 * (p4 & 1); } }
;     const bf16* vbase = vbuf + (size_t)(b * SEQ) * KVD + g * 128 + 8 * dg;
.LBB0_2272:
	s_or_b64 exec, exec, s[4:5]
	v_xor_b32_e32 v22, v24, v16
	v_lshlrev_b32_e32 v22, 4, v22
	v_lshlrev_b32_e32 v19, 8, v25
	v_lshlrev_b32_e32 v26, 8, v24
	v_and_b32_e32 v22, 0xf0, v22
	v_or_b32_e32 v27, v22, v26
	v_or_b32_e32 v28, v22, v19
	v_add_u32_e32 v22, 4, v24
	v_xor_b32_e32 v23, v22, v16
	v_lshlrev_b32_e32 v23, 4, v23
	v_and_b32_e32 v23, 0xf0, v23
	v_lshl_or_b32 v29, v22, 8, v23
	v_add_u32_e32 v22, 8, v24
	v_or_b32_e32 v30, v23, v19
	v_xor_b32_e32 v23, v22, v16
	v_lshlrev_b32_e32 v23, 4, v23
	v_readlane_b32 s10, v254, 7
	v_and_b32_e32 v23, 0xf0, v23
	v_readlane_b32 s11, v254, 8
	v_lshl_or_b32 v31, v22, 8, v23
	v_add_u32_e32 v22, 12, v24
	s_load_dwordx2 s[10:11], s[10:11], 0x108
	v_or_b32_e32 v32, v23, v19
	v_xor_b32_e32 v23, v22, v16
	v_readlane_b32 s9, v254, 20
	v_lshlrev_b32_e32 v23, 4, v23
	s_add_i32 s8, s9, 0x1800
	v_and_b32_e32 v23, 0xf0, v23
	v_lshlrev_b32_e32 v39, 3, v16
	v_readlane_b32 s4, v253, 43
	v_lshl_or_b32 v33, v22, 8, v23
	v_or_b32_e32 v34, v23, v19
	v_lshrrev_b32_e32 v19, 2, v25
	v_lshl_add_u32 v22, v24, 11, s8
	v_and_b32_e32 v39, 8, v39
	s_lshl_b32 s4, s4, 10
	s_lshl_b32 s5, s7, 8
	v_and_b32_e32 v35, 3, v16
	v_lshl_add_u32 v36, v19, 9, v22
	v_lshlrev_b32_e32 v23, 1, v24
	v_lshl_or_b32 v19, v19, 6, v39
	s_waitcnt lgkmcnt(0)
	s_add_u32 s4, s10, s4
	v_and_b32_e32 v37, 2, v23
	v_bfe_u32 v38, v16, 1, 1
	v_add_u32_e32 v19, v19, v22
	v_bitop3_b32 v22, v23, v35, 2 bitop3:0x6c
	s_addc_u32 s7, s11, 0
	v_lshlrev_b32_e32 v39, 4, v22
	v_or_b32_e32 v22, v37, v38
	v_bitop3_b32 v23, v38, v23, 2 bitop3:0x72
	s_add_u32 s4, s4, s5
	v_lshl_add_u32 v176, v22, 4, v19
	v_or_b32_e32 v22, 2, v38
	v_lshl_add_u32 v177, v23, 4, v19
	v_bitop3_b32 v23, v37, v35, 1 bitop3:0x36
	s_addc_u32 s5, s7, 0
	v_lshlrev_b32_e32 v40, 4, v23
	v_add_u32_e32 v19, 0x100, v19
	v_bitop3_b32 v23, v37, v38, 1 bitop3:0x36
	v_bitop3_b32 v22, v37, v22, 1 bitop3:0x36
	v_lshlrev_b32_e32 v132, 4, v25
	v_mov_b32_e32 v133, 0
	v_lshl_add_u32 v178, v23, 4, v19
	v_lshl_add_u32 v179, v22, 4, v19
	v_lshl_add_u64 v[22:23], s[4:5], 0, v[132:133]
	s_add_u32 s98, s4, 0x1e000000
	s_addc_u32 s99, s5, 0
	s_add_u32 s100, s4, 0x1f000000
	s_addc_u32 s101, s5, 0
	v_mov_b32_e32 v252, v132
	s_mov_b64 s[4:5], 0x1e000000
	v_lshl_add_u64 v[134:135], v[22:23], 0, s[4:5]
	s_mov_b64 s[4:5], 0x1f000000
	v_lshl_add_u64 v[136:137], v[22:23], 0, s[4:5]
	v_lshlrev_b32_e32 v19, 8, v35
	v_and_b32_e32 v22, -4, v16
	v_add3_u32 v181, s9, v19, v22
	v_mov_b32_e32 v19, v133
	v_lshl_add_u32 v180, v16, 2, s9
	v_lshl_add_u64 v[138:139], v[16:17], 2, s[0:1]
	v_lshl_add_u64 v[18:19], s[2:3], 0, v[18:19]
	v_cmp_gt_i32_e64 s[0:1], 16, v16
	v_lshlrev_b32_e32 v16, 1, v16
	v_lshl_add_u64 v[140:141], v[20:21], 1, v[18:19]
	v_sub_u32_e32 v18, 0, v16
	v_lshl_add_u32 v16, v24, 7, s6
	v_ashrrev_i32_e32 v17, 31, v16
	v_writelane_b32 v253, s0, 5
	v_lshl_add_u64 v[16:17], v[16:17], 1, s[10:11]
	v_lshl_add_u64 v[16:17], v[16:17], 0, v[132:133]
	v_writelane_b32 v253, s1, 6
	s_mov_b64 s[0:1], 0x42400000
	v_add_u32_e32 v182, s9, v26
	v_lshlrev_b32_e32 v183, 6, v24
	v_lshl_add_u64 v[142:143], v[16:17], 0, s[0:1]
	v_mbcnt_lo_u32_b32 v16, -1, 0
	v_add_u32_e32 v184, v182, v132
	v_or_b32_e32 v132, 21, v183
	v_or_b32_e32 v185, 22, v183
	v_or_b32_e32 v186, 23, v183
	v_or_b32_e32 v187, 24, v183
	v_or_b32_e32 v188, 25, v183
	v_or_b32_e32 v189, 26, v183
	v_or_b32_e32 v190, 27, v183
	v_or_b32_e32 v191, 28, v183
	v_or_b32_e32 v192, 29, v183
	v_or_b32_e32 v193, 30, v183
	v_or_b32_e32 v194, 31, v183
	v_or_b32_e32 v195, 32, v183
	v_or_b32_e32 v196, 33, v183
	v_or_b32_e32 v197, 34, v183
	v_or_b32_e32 v198, 35, v183
	v_or_b32_e32 v199, 36, v183
	v_or_b32_e32 v200, 37, v183
	v_or_b32_e32 v201, 38, v183
	v_or_b32_e32 v202, 39, v183
	v_or_b32_e32 v203, 40, v183
	v_or_b32_e32 v204, 41, v183
	v_or_b32_e32 v205, 42, v183
	v_or_b32_e32 v206, 43, v183
	v_or_b32_e32 v207, 44, v183
	v_or_b32_e32 v208, 45, v183
	v_or_b32_e32 v209, 46, v183
	v_or_b32_e32 v210, 47, v183
	v_or_b32_e32 v211, 48, v183
	v_or_b32_e32 v212, 49, v183
	v_or_b32_e32 v213, 50, v183
	v_or_b32_e32 v214, 51, v183
	v_or_b32_e32 v215, 52, v183
	v_or_b32_e32 v216, 53, v183
	v_or_b32_e32 v217, 54, v183
	v_or_b32_e32 v218, 55, v183
	v_or_b32_e32 v219, 56, v183
	v_or_b32_e32 v220, 57, v183
	v_or_b32_e32 v221, 58, v183
	v_or_b32_e32 v222, 59, v183
	v_or_b32_e32 v223, 60, v183
	v_or_b32_e32 v224, 61, v183
	v_or_b32_e32 v225, 62, v183
	v_or_b32_e32 v226, 63, v183
	v_add_u32_e32 v227, s9, v27
	v_add_u32_e32 v228, s9, v29
	v_add_u32_e32 v229, s9, v31
	v_add_u32_e32 v230, s9, v33
	v_add_u32_e32 v231, s9, v28
	v_add_u32_e32 v232, s9, v30
	v_add_u32_e32 v233, s9, v32
	v_add_u32_e32 v234, s9, v34
	s_mov_b32 s78, 0x3db504f3
	v_mbcnt_hi_u32_b32 v235, -1, v16
	v_add_u32_e32 v236, v39, v36
	v_add_u32_e32 v237, v40, v36
	s_movk_i32 s79, 0x7fff
	v_add_u32_e32 v238, v180, v18
	v_mov_b32_e32 v239, 0xff61b1e6
	s_branch .LBB0_2274

; #define LAS __attribute__((address_space(3)))
; #define ATT_KISSUE(slot_, hg_) do { v2i kx_[4]; \
;             _Pragma("unroll") for (int i = 0; i < 4; ++i) kx_[i] = *(const LAS v2i*)(idl2 + rg * 64 + 16 * i + 2 * (hg_)); \
;             _Pragma("unroll") for (int j = 0; j < 2; ++j) _Pragma("unroll") for (int i = 0; i < 4; ++i) kf[slot_][j][i] = *(const v4u*)(kvb + (size_t)kx_[i][j] * KVD); \
;             ATT_FENCE(); } while (0)
; DI void attn_worker(unsigned char* ws, LAS unsigned char* lds, LAS unsigned* qctr, int wave) {
;     ...
;         f32x4 s[16]; v4u kf[3][2][4];
;     ...
;         ATT_KISSUE(0, 0); ATT_KISSUE(1, 1);
; #pragma unroll
;         for (int hg = 0; hg < 8; ++hg) {
;             if (hg + 2 < 8) ATT_KISSUE((hg + 2) % 3, hg + 2);
; #pragma unroll
;             for (int j = 0; j < 2; ++j) {
; #pragma unroll
;                 for (int i = 0; i < 4; ++i) *(LAS v4u*)(stg + j * 4096 + woff[i]) = kf[hg % 3][j][i];
;                 bf16x8 ka[4];
; #pragma unroll
;                 for (int ks = 0; ks < 4; ++ks) ka[ks] = *(const LAS bf16x8*)(stg + j * 4096 + roff[ks]);
;                 f32x4 a = {0.f, 0.f, 0.f, 0.f};
; #pragma unroll
;                 for (int ks = 0; ks < 4; ++ks) a = __builtin_amdgcn_mfma_f32_16x16x32_bf16(ka[ks], qf[ks], a, 0, 0, 0);
;                 s[2 * hg + j] = a; }
;         }
.LBB0_2280:
	ds_read2_b64 v[16:19], v182 offset0:128 offset1:136
	ds_read2_b64 v[20:23], v182 offset0:144 offset1:152
	s_waitcnt lgkmcnt(1)
	v_lshl_add_u32 v24, v16, 10, v252
	v_lshl_add_u32 v26, v18, 10, v252
	v_mov_b32_e32 v28, v24
	v_mov_b32_e32 v24, v26
	v_mov_b32_e32 v30, v24
	global_load_dwordx4 v[24:27], v28, s[98:99]
	global_load_dwordx4 v[60:63], v30, s[98:99]
	s_waitcnt lgkmcnt(0)
	v_lshl_add_u32 v28, v20, 10, v252
	v_lshl_add_u32 v30, v22, 10, v252
	global_load_dwordx4 v[72:75], v28, s[98:99]
	global_load_dwordx4 v[84:87], v30, s[98:99]
	v_lshl_add_u32 v28, v17, 10, v252
	v_lshl_add_u32 v16, v19, 10, v252
	v_mov_b32_e32 v30, v16
	global_load_dwordx4 v[16:19], v28, s[98:99]
	global_load_dwordx4 v[88:91], v30, s[98:99]
	v_lshl_add_u32 v28, v21, 10, v252
	v_mov_b32_e32 v20, v28
	v_lshl_add_u32 v28, v23, 10, v252
	global_load_dwordx4 v[20:23], v20, s[98:99]
	s_nop 0
	global_load_dwordx4 v[96:99], v28, s[98:99]
	ds_read2_b64 v[28:31], v182 offset0:129 offset1:137
	ds_read2_b64 v[48:51], v182 offset0:145 offset1:153
	s_waitcnt lgkmcnt(1)
	v_lshl_add_u32 v32, v28, 10, v252
	v_lshl_add_u32 v34, v30, 10, v252
	s_waitcnt lgkmcnt(0)
	v_lshl_add_u32 v40, v48, 10, v252
	v_lshl_add_u32 v42, v50, 10, v252
	v_mov_b32_e32 v36, v34
	global_load_dwordx4 v[32:35], v32, s[98:99]
	s_nop 0
	global_load_dwordx4 v[36:39], v36, s[98:99]
	v_mov_b32_e32 v44, v42
	global_load_dwordx4 v[40:43], v40, s[98:99]
	s_nop 0
	global_load_dwordx4 v[80:83], v44, s[98:99]
	v_lshl_add_u32 v44, v29, 10, v252
	v_mov_b32_e32 v28, v44
	v_lshl_add_u32 v44, v31, 10, v252
	v_mov_b32_e32 v30, v44
	global_load_dwordx4 v[44:47], v28, s[98:99]
	global_load_dwordx4 v[68:71], v30, s[98:99]
	v_lshl_add_u32 v28, v49, 10, v252
	v_lshl_add_u32 v30, v51, 10, v252
	global_load_dwordx4 v[100:103], v28, s[98:99]
	global_load_dwordx4 v[108:111], v30, s[98:99]
	ds_read2_b64 v[52:55], v182 offset0:130 offset1:138
	ds_read2_b64 v[92:95], v182 offset0:146 offset1:154
	s_waitcnt lgkmcnt(1)
	v_lshl_add_u32 v28, v52, 10, v252
	v_lshl_add_u32 v30, v54, 10, v252
	s_waitcnt lgkmcnt(0)
	v_lshl_add_u32 v56, v92, 10, v252
	v_lshl_add_u32 v58, v94, 10, v252
	v_mov_b32_e32 v48, v30
	global_load_dwordx4 v[28:31], v28, s[98:99]
	s_nop 0
	global_load_dwordx4 v[48:51], v48, s[98:99]
	global_load_dwordx4 v[64:67], v56, s[98:99]
	global_load_dwordx4 v[76:79], v58, s[98:99]
	v_lshl_add_u32 v56, v53, 10, v252
	v_lshl_add_u32 v104, v93, 10, v252
	v_mov_b32_e32 v52, v56
	v_lshl_add_u32 v56, v55, 10, v252
	v_mov_b32_e32 v92, v104
	v_lshl_add_u32 v104, v95, 10, v252
	global_load_dwordx4 v[52:55], v52, s[98:99]
	s_nop 0
	global_load_dwordx4 v[56:59], v56, s[98:99]
	s_nop 0
	global_load_dwordx4 v[92:95], v92, s[98:99]
	s_nop 0
	global_load_dwordx4 v[104:107], v104, s[98:99]
	s_waitcnt vmcnt(23)
	ds_write_b128 v227, v[24:27] offset:6144
	s_waitcnt vmcnt(22)
	ds_write_b128 v228, v[60:63] offset:6144
	s_waitcnt vmcnt(21)
	ds_write_b128 v229, v[72:75] offset:6144
	s_waitcnt vmcnt(20)
	ds_write_b128 v230, v[84:87] offset:6144
	ds_read_b128 v[24:27], v231 offset:6144
	ds_read_b128 v[60:63], v232 offset:6144
	s_waitcnt lgkmcnt(1)
	v_mfma_f32_16x16x32_bf16 v[24:27], v[24:27], v[4:7], 0
	s_waitcnt lgkmcnt(0)
	v_mfma_f32_16x16x32_bf16 v[24:27], v[60:63], v[0:3], v[24:27]
	ds_read_b128 v[60:63], v233 offset:6144
	ds_read_b128 v[72:75], v234 offset:6144
	s_waitcnt vmcnt(19)
	ds_write_b128 v227, v[16:19] offset:10240
	s_waitcnt vmcnt(18)
	ds_write_b128 v228, v[88:91] offset:10240
	s_waitcnt vmcnt(17)
	ds_write_b128 v229, v[20:23] offset:10240
	s_waitcnt vmcnt(16)
	ds_write_b128 v230, v[96:99] offset:10240
	ds_read_b128 v[16:19], v231 offset:10240
	ds_read_b128 v[20:23], v232 offset:10240
	s_waitcnt lgkmcnt(7)
	v_mfma_f32_16x16x32_bf16 v[24:27], v[60:63], v[12:15], v[24:27]
	ds_read_b128 v[60:63], v233 offset:10240
	s_waitcnt lgkmcnt(2)
	v_mfma_f32_16x16x32_bf16 v[16:19], v[16:19], v[4:7], 0
	v_mfma_f32_16x16x32_bf16 v[24:27], v[72:75], v[8:11], v[24:27]
	ds_read2_b64 v[72:75], v182 offset0:131 offset1:139
	ds_read_b128 v[88:91], v234 offset:10240
	ds_read2_b64 v[116:119], v182 offset0:147 offset1:155
	s_waitcnt lgkmcnt(0)
	v_mfma_f32_16x16x32_bf16 v[16:19], v[20:23], v[0:3], v[16:19]
	v_lshl_add_u32 v120, v117, 10, v252
	v_mfma_f32_16x16x32_bf16 v[112:115], v[60:63], v[12:15], v[16:19]
	v_lshl_add_u32 v60, v116, 10, v252
	s_nop 2
	v_lshl_add_u32 v16, v72, 10, v252
	v_lshl_add_u32 v18, v74, 10, v252
	v_lshl_add_u32 v62, v118, 10, v252
	v_mov_b32_e32 v20, v18
	global_load_dwordx4 v[16:19], v16, s[98:99]
	s_nop 0
	global_load_dwordx4 v[20:23], v20, s[98:99]
	s_nop 0
	global_load_dwordx4 v[84:87], v60, s[98:99]
	global_load_dwordx4 v[96:99], v62, s[98:99]
	v_lshl_add_u32 v60, v73, 10, v252
	v_lshl_add_u32 v62, v75, 10, v252
	v_mov_b32_e32 v116, v120
	v_lshl_add_u32 v120, v119, 10, v252
	v_mov_b32_e32 v72, v62
	global_load_dwordx4 v[60:63], v60, s[98:99]
	s_nop 0
	global_load_dwordx4 v[72:75], v72, s[98:99]
	global_load_dwordx4 v[116:119], v116, s[98:99]
	s_nop 0
	global_load_dwordx4 v[124:127], v120, s[98:99]
	s_waitcnt vmcnt(23)
	ds_write_b128 v227, v[32:35] offset:6144
	s_waitcnt vmcnt(22)
	ds_write_b128 v228, v[36:39] offset:6144
	s_waitcnt vmcnt(21)
	ds_write_b128 v229, v[40:43] offset:6144
	s_waitcnt vmcnt(20)
	ds_write_b128 v230, v[80:83] offset:6144
	ds_read_b128 v[32:35], v231 offset:6144
	ds_read_b128 v[36:39], v232 offset:6144
	s_waitcnt lgkmcnt(1)
	v_mfma_f32_16x16x32_bf16 v[32:35], v[32:35], v[4:7], 0
	s_waitcnt lgkmcnt(0)
	v_mfma_f32_16x16x32_bf16 v[32:35], v[36:39], v[0:3], v[32:35]
	ds_read_b128 v[36:39], v233 offset:6144
	ds_read_b128 v[80:83], v234 offset:6144
	s_waitcnt vmcnt(19)
	ds_write_b128 v227, v[44:47] offset:10240
	s_waitcnt vmcnt(18)
; #define LAS __attribute__((address_space(3)))
; #define ATT_KISSUE(slot_, hg_) do { v2i kx_[4]; \
;             _Pragma("unroll") for (int i = 0; i < 4; ++i) kx_[i] = *(const LAS v2i*)(idl2 + rg * 64 + 16 * i + 2 * (hg_)); \
;             _Pragma("unroll") for (int j = 0; j < 2; ++j) _Pragma("unroll") for (int i = 0; i < 4; ++i) kf[slot_][j][i] = *(const v4u*)(kvb + (size_t)kx_[i][j] * KVD); \
;             ATT_FENCE(); } while (0)
; DI void attn_worker(unsigned char* ws, LAS unsigned char* lds, LAS unsigned* qctr, int wave) {
;     ...
;         f32x4 s[16]; v4u kf[3][2][4];
;     ...
;         ATT_KISSUE(0, 0); ATT_KISSUE(1, 1);
; #pragma unroll
;         for (int hg = 0; hg < 8; ++hg) {
;             if (hg + 2 < 8) ATT_KISSUE((hg + 2) % 3, hg + 2);
; #pragma unroll
;             for (int j = 0; j < 2; ++j) {
; #pragma unroll
;                 for (int i = 0; i < 4; ++i) *(LAS v4u*)(stg + j * 4096 + woff[i]) = kf[hg % 3][j][i];
;                 bf16x8 ka[4];
; #pragma unroll
;                 for (int ks = 0; ks < 4; ++ks) ka[ks] = *(const LAS bf16x8*)(stg + j * 4096 + roff[ks]);
;                 f32x4 a = {0.f, 0.f, 0.f, 0.f};
; #pragma unroll
;                 for (int ks = 0; ks < 4; ++ks) a = __builtin_amdgcn_mfma_f32_16x16x32_bf16(ka[ks], qf[ks], a, 0, 0, 0);
;                 s[2 * hg + j] = a; }
;         }
	ds_write_b128 v228, v[68:71] offset:10240
	s_waitcnt vmcnt(17)
	ds_write_b128 v229, v[100:103] offset:10240
	s_waitcnt vmcnt(16)
	ds_write_b128 v230, v[108:111] offset:10240
	ds_read_b128 v[68:71], v233 offset:10240
	s_waitcnt lgkmcnt(6)
	v_mfma_f32_16x16x32_bf16 v[32:35], v[36:39], v[12:15], v[32:35]
	ds_read_b128 v[36:39], v231 offset:10240
	s_waitcnt lgkmcnt(6)
	v_mfma_f32_16x16x32_bf16 v[44:47], v[80:83], v[8:11], v[32:35]
	s_nop 4
	ds_read_b128 v[32:35], v232 offset:10240
	s_waitcnt lgkmcnt(1)
	v_mfma_f32_16x16x32_bf16 v[36:39], v[36:39], v[4:7], 0
	ds_read2_b64 v[80:83], v182 offset0:132 offset1:140
	ds_read_b128 v[108:111], v234 offset:10240
	ds_read2_b64 v[120:123], v182 offset0:148 offset1:156
	s_waitcnt lgkmcnt(0)
	v_mfma_f32_16x16x32_bf16 v[32:35], v[32:35], v[0:3], v[36:39]
	v_lshl_add_u32 v128, v121, 10, v252
	v_mfma_f32_16x16x32_bf16 v[40:43], v[88:91], v[8:11], v[112:115]
	v_mfma_f32_16x16x32_bf16 v[112:115], v[68:71], v[12:15], v[32:35]
	v_lshl_add_u32 v68, v120, 10, v252
	s_nop 1
	v_lshl_add_u32 v32, v80, 10, v252
	v_lshl_add_u32 v34, v82, 10, v252
	v_lshl_add_u32 v70, v122, 10, v252
	v_mov_b32_e32 v36, v34
	global_load_dwordx4 v[32:35], v32, s[98:99]
	s_nop 0
	global_load_dwordx4 v[36:39], v36, s[98:99]
	global_load_dwordx4 v[88:91], v68, s[98:99]
	global_load_dwordx4 v[100:103], v70, s[98:99]
	v_lshl_add_u32 v68, v81, 10, v252
	v_lshl_add_u32 v70, v83, 10, v252
	v_mov_b32_e32 v120, v128
	v_lshl_add_u32 v128, v123, 10, v252
	v_mov_b32_e32 v80, v70
	global_load_dwordx4 v[68:71], v68, s[98:99]
	s_nop 0
	global_load_dwordx4 v[80:83], v80, s[98:99]
	s_nop 0
	global_load_dwordx4 v[120:123], v120, s[98:99]
	s_nop 0
	global_load_dwordx4 v[128:131], v128, s[98:99]
	s_waitcnt vmcnt(23)
	ds_write_b128 v227, v[28:31] offset:6144
	s_waitcnt vmcnt(22)
	ds_write_b128 v228, v[48:51] offset:6144
	s_waitcnt vmcnt(21)
	ds_write_b128 v229, v[64:67] offset:6144
	s_waitcnt vmcnt(20)
	ds_write_b128 v230, v[76:79] offset:6144
	ds_read_b128 v[28:31], v231 offset:6144
	ds_read_b128 v[48:51], v232 offset:6144
	s_waitcnt lgkmcnt(1)
	v_mfma_f32_16x16x32_bf16 v[28:31], v[28:31], v[4:7], 0
	s_waitcnt lgkmcnt(0)
	v_mfma_f32_16x16x32_bf16 v[28:31], v[48:51], v[0:3], v[28:31]
	ds_read_b128 v[48:51], v233 offset:6144
	ds_read_b128 v[64:67], v234 offset:6144
	s_waitcnt vmcnt(19)
	ds_write_b128 v227, v[52:55] offset:10240
	s_waitcnt vmcnt(18)
	ds_write_b128 v228, v[56:59] offset:10240
	s_waitcnt vmcnt(17)
	ds_write_b128 v229, v[92:95] offset:10240
	s_waitcnt vmcnt(16)
	ds_write_b128 v230, v[104:107] offset:10240
	ds_read_b128 v[52:55], v232 offset:10240
	s_waitcnt lgkmcnt(6)
	v_mfma_f32_16x16x32_bf16 v[28:31], v[48:51], v[12:15], v[28:31]
	ds_read_b128 v[48:51], v231 offset:10240
	ds_read_b128 v[56:59], v233 offset:10240
	s_waitcnt lgkmcnt(1)
	v_mfma_f32_16x16x32_bf16 v[48:51], v[48:51], v[4:7], 0
	v_mfma_f32_16x16x32_bf16 v[76:79], v[108:111], v[8:11], v[112:115]
	v_mfma_f32_16x16x32_bf16 v[28:31], v[64:67], v[8:11], v[28:31]
	ds_read2_b64 v[64:67], v182 offset0:133 offset1:141
	ds_read_b128 v[144:147], v234 offset:10240
	ds_read2_b64 v[108:111], v182 offset0:149 offset1:157
	s_waitcnt lgkmcnt(0)
	v_mfma_f32_16x16x32_bf16 v[48:51], v[52:55], v[0:3], v[48:51]
	v_lshl_add_u32 v112, v109, 10, v252
	v_mfma_f32_16x16x32_bf16 v[148:151], v[56:59], v[12:15], v[48:51]
	v_lshl_add_u32 v56, v108, 10, v252
	s_nop 2
	v_lshl_add_u32 v48, v64, 10, v252
	v_lshl_add_u32 v50, v66, 10, v252
	v_lshl_add_u32 v58, v110, 10, v252
	v_mov_b32_e32 v52, v50
	global_load_dwordx4 v[48:51], v48, s[98:99]
	s_nop 0
	global_load_dwordx4 v[52:55], v52, s[98:99]
	s_nop 0
	global_load_dwordx4 v[92:95], v56, s[98:99]
	global_load_dwordx4 v[104:107], v58, s[98:99]
	v_lshl_add_u32 v56, v65, 10, v252
	v_lshl_add_u32 v58, v67, 10, v252
	v_mov_b32_e32 v108, v112
	v_lshl_add_u32 v112, v111, 10, v252
	v_mov_b32_e32 v64, v58
	global_load_dwordx4 v[56:59], v56, s[98:99]
	s_nop 0
	global_load_dwordx4 v[64:67], v64, s[98:99]
	s_nop 0
	global_load_dwordx4 v[108:111], v108, s[98:99]
	s_nop 0
	global_load_dwordx4 v[112:115], v112, s[98:99]
	s_waitcnt vmcnt(23)
	ds_write_b128 v227, v[16:19] offset:6144
	s_waitcnt vmcnt(22)
	ds_write_b128 v228, v[20:23] offset:6144
	s_waitcnt vmcnt(21)
	ds_write_b128 v229, v[84:87] offset:6144
	s_waitcnt vmcnt(20)
	ds_write_b128 v230, v[96:99] offset:6144
	ds_read_b128 v[20:23], v231 offset:6144
	ds_read_b128 v[84:87], v232 offset:6144
	s_waitcnt lgkmcnt(1)
	v_mfma_f32_16x16x32_bf16 v[20:23], v[20:23], v[4:7], 0
	s_waitcnt lgkmcnt(0)
	v_mfma_f32_16x16x32_bf16 v[20:23], v[84:87], v[0:3], v[20:23]
	ds_read_b128 v[84:87], v233 offset:6144
	ds_read_b128 v[96:99], v234 offset:6144
	s_waitcnt vmcnt(19)
	ds_write_b128 v227, v[60:63] offset:10240
	s_waitcnt vmcnt(18)
	ds_write_b128 v228, v[72:75] offset:10240
	s_waitcnt vmcnt(17)
	ds_write_b128 v229, v[116:119] offset:10240
	s_waitcnt vmcnt(16)
	ds_write_b128 v230, v[124:127] offset:10240
	ds_read_b128 v[60:63], v231 offset:10240
	ds_read_b128 v[72:75], v232 offset:10240
	s_waitcnt lgkmcnt(7)
	v_mfma_f32_16x16x32_bf16 v[20:23], v[84:87], v[12:15], v[20:23]
	ds_read_b128 v[84:87], v233 offset:10240
	s_waitcnt lgkmcnt(7)
	v_mfma_f32_16x16x32_bf16 v[20:23], v[96:99], v[8:11], v[20:23]
	ds_read2_b64 v[96:99], v182 offset0:134 offset1:142
	ds_read_b128 v[116:119], v234 offset:10240
	ds_read2_b64 v[124:127], v182 offset0:150 offset1:158
	s_waitcnt lgkmcnt(2)
	v_mfma_f32_16x16x32_bf16 v[60:63], v[60:63], v[4:7], 0
	v_lshl_add_u32 v152, v97, 10, v252
	s_waitcnt lgkmcnt(0)
; #define LAS __attribute__((address_space(3)))
; #define ATT_KISSUE(slot_, hg_) do { v2i kx_[4]; \
;             _Pragma("unroll") for (int i = 0; i < 4; ++i) kx_[i] = *(const LAS v2i*)(idl2 + rg * 64 + 16 * i + 2 * (hg_)); \
;             _Pragma("unroll") for (int j = 0; j < 2; ++j) _Pragma("unroll") for (int i = 0; i < 4; ++i) kf[slot_][j][i] = *(const v4u*)(kvb + (size_t)kx_[i][j] * KVD); \
;             ATT_FENCE(); } while (0)
; DI void attn_worker(unsigned char* ws, LAS unsigned char* lds, LAS unsigned* qctr, int wave) {
;     ...
;         f32x4 s[16]; v4u kf[3][2][4];
;     ...
;         ATT_KISSUE(0, 0); ATT_KISSUE(1, 1);
; #pragma unroll
;         for (int hg = 0; hg < 8; ++hg) {
;             if (hg + 2 < 8) ATT_KISSUE((hg + 2) % 3, hg + 2);
; #pragma unroll
;             for (int j = 0; j < 2; ++j) {
; #pragma unroll
;                 for (int i = 0; i < 4; ++i) *(LAS v4u*)(stg + j * 4096 + woff[i]) = kf[hg % 3][j][i];
;                 bf16x8 ka[4];
; #pragma unroll
;                 for (int ks = 0; ks < 4; ++ks) ka[ks] = *(const LAS bf16x8*)(stg + j * 4096 + roff[ks]);
;                 f32x4 a = {0.f, 0.f, 0.f, 0.f};
; #pragma unroll
;                 for (int ks = 0; ks < 4; ++ks) a = __builtin_amdgcn_mfma_f32_16x16x32_bf16(ka[ks], qf[ks], a, 0, 0, 0);
;                 s[2 * hg + j] = a; }
;         }
	v_lshl_add_u32 v156, v125, 10, v252
	v_mfma_f32_16x16x32_bf16 v[60:63], v[72:75], v[0:3], v[60:63]
	v_lshl_add_u32 v72, v96, 10, v252
	v_mfma_f32_16x16x32_bf16 v[16:19], v[144:147], v[8:11], v[148:151]
	v_lshl_add_u32 v74, v98, 10, v252
	v_lshl_add_u32 v144, v124, 10, v252
	v_lshl_add_u32 v146, v126, 10, v252
	v_mov_b32_e32 v96, v152
	v_lshl_add_u32 v152, v99, 10, v252
	v_mov_b32_e32 v124, v156
	v_lshl_add_u32 v156, v127, 10, v252
	v_mfma_f32_16x16x32_bf16 v[60:63], v[84:87], v[12:15], v[60:63]
	v_mov_b32_e32 v84, v74
	v_mov_b32_e32 v148, v146
	global_load_dwordx4 v[72:75], v72, s[98:99]
	s_nop 0
	global_load_dwordx4 v[84:87], v84, s[98:99]
	s_nop 0
	global_load_dwordx4 v[144:147], v144, s[98:99]
	s_nop 0
	global_load_dwordx4 v[148:151], v148, s[98:99]
	s_nop 0
	global_load_dwordx4 v[96:99], v96, s[98:99]
	s_nop 0
	global_load_dwordx4 v[152:155], v152, s[98:99]
	s_nop 0
	global_load_dwordx4 v[124:127], v124, s[98:99]
	s_nop 0
	global_load_dwordx4 v[156:159], v156, s[98:99]
	s_waitcnt vmcnt(23)
	ds_write_b128 v227, v[32:35] offset:6144
	s_waitcnt vmcnt(22)
	ds_write_b128 v228, v[36:39] offset:6144
	s_waitcnt vmcnt(21)
	ds_write_b128 v229, v[88:91] offset:6144
	s_waitcnt vmcnt(20)
	ds_write_b128 v230, v[100:103] offset:6144
	ds_read_b128 v[32:35], v231 offset:6144
	v_mfma_f32_16x16x32_bf16 v[36:39], v[116:119], v[8:11], v[60:63]
	s_nop 2
	ds_read_b128 v[60:63], v232 offset:6144
	s_waitcnt lgkmcnt(1)
	v_mfma_f32_16x16x32_bf16 v[32:35], v[32:35], v[4:7], 0
	s_waitcnt lgkmcnt(0)
	v_mfma_f32_16x16x32_bf16 v[32:35], v[60:63], v[0:3], v[32:35]
	ds_read_b128 v[60:63], v233 offset:6144
	ds_read_b128 v[88:91], v234 offset:6144
	s_waitcnt vmcnt(19)
	ds_write_b128 v227, v[68:71] offset:10240
	s_waitcnt vmcnt(18)
	ds_write_b128 v228, v[80:83] offset:10240
	s_waitcnt vmcnt(17)
	ds_write_b128 v229, v[120:123] offset:10240
	s_waitcnt vmcnt(16)
	ds_write_b128 v230, v[128:131] offset:10240
	ds_read_b128 v[68:71], v232 offset:10240
	s_waitcnt lgkmcnt(6)
	v_mfma_f32_16x16x32_bf16 v[32:35], v[60:63], v[12:15], v[32:35]
	ds_read_b128 v[60:63], v231 offset:10240
	ds_read_b128 v[80:83], v233 offset:10240
	s_waitcnt lgkmcnt(1)
	v_mfma_f32_16x16x32_bf16 v[60:63], v[60:63], v[4:7], 0
	v_mfma_f32_16x16x32_bf16 v[60:63], v[68:71], v[0:3], v[60:63]
	v_mfma_f32_16x16x32_bf16 v[32:35], v[88:91], v[8:11], v[32:35]
	ds_read2_b64 v[68:71], v182 offset0:135 offset1:143
	ds_read_b128 v[88:91], v234 offset:10240
	s_waitcnt lgkmcnt(1)
	v_mfma_f32_16x16x32_bf16 v[60:63], v[80:83], v[12:15], v[60:63]
	ds_read2_b64 v[80:83], v182 offset0:151 offset1:159
	v_lshl_add_u32 v100, v68, 10, v252
	v_lshl_add_u32 v102, v70, 10, v252
	s_waitcnt lgkmcnt(0)
	v_lshl_add_u32 v120, v80, 10, v252
	v_lshl_add_u32 v122, v82, 10, v252
	v_mov_b32_e32 v116, v102
	v_mov_b32_e32 v128, v122
	global_load_dwordx4 v[100:103], v100, s[98:99]
	s_nop 0
	global_load_dwordx4 v[116:119], v116, s[98:99]
	s_nop 0
	global_load_dwordx4 v[120:123], v120, s[98:99]
	s_nop 0
	global_load_dwordx4 v[128:131], v128, s[98:99]
	v_lshl_add_u32 v160, v69, 10, v252
	v_lshl_add_u32 v164, v81, 10, v252
	v_mov_b32_e32 v68, v160
	v_lshl_add_u32 v160, v71, 10, v252
	v_mov_b32_e32 v80, v164
	v_lshl_add_u32 v164, v83, 10, v252
	global_load_dwordx4 v[68:71], v68, s[98:99]
	s_nop 0
	global_load_dwordx4 v[160:163], v160, s[98:99]
	s_nop 0
	global_load_dwordx4 v[80:83], v80, s[98:99]
	s_nop 0
	global_load_dwordx4 v[164:167], v164, s[98:99]
	s_waitcnt vmcnt(23)
	ds_write_b128 v227, v[48:51] offset:6144
	s_waitcnt vmcnt(22)
	ds_write_b128 v228, v[52:55] offset:6144
	s_waitcnt vmcnt(21)
	ds_write_b128 v229, v[92:95] offset:6144
	s_waitcnt vmcnt(20)
	ds_write_b128 v230, v[104:107] offset:6144
	ds_read_b128 v[48:51], v231 offset:6144
	ds_read_b128 v[52:55], v232 offset:6144
	s_waitcnt lgkmcnt(1)
	v_mfma_f32_16x16x32_bf16 v[48:51], v[48:51], v[4:7], 0
	v_mfma_f32_16x16x32_bf16 v[60:63], v[88:91], v[8:11], v[60:63]
	s_waitcnt lgkmcnt(0)
	v_mfma_f32_16x16x32_bf16 v[48:51], v[52:55], v[0:3], v[48:51]
	ds_read_b128 v[52:55], v233 offset:6144
	ds_read_b128 v[88:91], v234 offset:6144
	s_waitcnt vmcnt(19)
	ds_write_b128 v227, v[56:59] offset:10240
	s_waitcnt vmcnt(18)
	ds_write_b128 v228, v[64:67] offset:10240
	s_waitcnt vmcnt(17)
	ds_write_b128 v229, v[108:111] offset:10240
	s_waitcnt vmcnt(16)
	ds_write_b128 v230, v[112:115] offset:10240
	ds_read_b128 v[56:59], v231 offset:10240
	s_waitcnt lgkmcnt(6)
	v_mfma_f32_16x16x32_bf16 v[48:51], v[52:55], v[12:15], v[48:51]
	s_waitcnt lgkmcnt(5)
	v_mfma_f32_16x16x32_bf16 v[52:55], v[88:91], v[8:11], v[48:51]
	s_nop 5
	ds_read_b128 v[48:51], v232 offset:10240
	s_waitcnt lgkmcnt(1)
	v_mfma_f32_16x16x32_bf16 v[56:59], v[56:59], v[4:7], 0
	s_waitcnt lgkmcnt(0)
	v_mfma_f32_16x16x32_bf16 v[48:51], v[48:51], v[0:3], v[56:59]
	s_nop 5
	ds_read_b128 v[56:59], v233 offset:10240
	ds_read_b128 v[64:67], v234 offset:10240
	s_waitcnt vmcnt(15)
	ds_write_b128 v227, v[72:75] offset:6144
	s_waitcnt vmcnt(14)
	ds_write_b128 v228, v[84:87] offset:6144
	s_waitcnt vmcnt(13)
	ds_write_b128 v229, v[144:147] offset:6144
	s_waitcnt vmcnt(12)
	ds_write_b128 v230, v[148:151] offset:6144
	s_waitcnt lgkmcnt(5)
	v_mfma_f32_16x16x32_bf16 v[48:51], v[56:59], v[12:15], v[48:51]
	ds_read_b128 v[56:59], v231 offset:6144
	s_waitcnt lgkmcnt(5)
	v_mfma_f32_16x16x32_bf16 v[48:51], v[64:67], v[8:11], v[48:51]
	ds_read_b128 v[64:67], v232 offset:6144
	s_waitcnt lgkmcnt(1)
	v_mfma_f32_16x16x32_bf16 v[56:59], v[56:59], v[4:7], 0
	s_waitcnt lgkmcnt(0)
	v_mfma_f32_16x16x32_bf16 v[56:59], v[64:67], v[0:3], v[56:59]
	ds_read_b128 v[64:67], v233 offset:6144
	ds_read_b128 v[72:75], v234 offset:6144
	s_waitcnt vmcnt(11)
	ds_write_b128 v227, v[96:99] offset:10240
	s_waitcnt vmcnt(10)
; DI void attn_worker(unsigned char* ws, LAS unsigned char* lds, LAS unsigned* qctr, int wave) {
;     ...
;         }
;     ...
;         if (qn2 < SEQ && kr < 4) { const int mq2 = b * SEQ + qn2;
; #pragma unroll
;             for (int ks = 0; ks < 4; ++ks) qf[ks] = *(const bf16x8*)(q + (size_t)mq2 * DA + (4 * g + kr) * 128 + 32 * ks + 8 * kq); }
;     ...
;             for (int e = 0; e < 4; ++e) { const bool ok = (64 * kq + 4 * kt + e) < nvalid; s[kt][e] = ok ? s[kt][e] * 0.08838834764831845f : -3.0e38f; mx = fmaxf(mx, s[kt][e]); }
	ds_write_b128 v228, v[152:155] offset:10240
	s_waitcnt vmcnt(9)
	ds_write_b128 v229, v[124:127] offset:10240
	s_waitcnt vmcnt(8)
	ds_write_b128 v230, v[156:159] offset:10240
	s_waitcnt lgkmcnt(5)
	v_mfma_f32_16x16x32_bf16 v[56:59], v[64:67], v[12:15], v[56:59]
	ds_read_b128 v[64:67], v231 offset:10240
	s_waitcnt lgkmcnt(5)
	v_mfma_f32_16x16x32_bf16 v[56:59], v[72:75], v[8:11], v[56:59]
	ds_read_b128 v[72:75], v232 offset:10240
	s_waitcnt lgkmcnt(1)
	v_mfma_f32_16x16x32_bf16 v[64:67], v[64:67], v[4:7], 0
	s_waitcnt lgkmcnt(0)
	v_mfma_f32_16x16x32_bf16 v[64:67], v[72:75], v[0:3], v[64:67]
	ds_read_b128 v[72:75], v233 offset:10240
	ds_read_b128 v[84:87], v234 offset:10240
	s_waitcnt vmcnt(7)
	ds_write_b128 v227, v[100:103] offset:6144
	s_waitcnt vmcnt(6)
	ds_write_b128 v228, v[116:119] offset:6144
	s_waitcnt vmcnt(5)
	ds_write_b128 v229, v[120:123] offset:6144
	s_waitcnt vmcnt(4)
	ds_write_b128 v230, v[128:131] offset:6144
	s_waitcnt lgkmcnt(5)
	v_mfma_f32_16x16x32_bf16 v[64:67], v[72:75], v[12:15], v[64:67]
	ds_read_b128 v[72:75], v231 offset:6144
	s_waitcnt lgkmcnt(5)
	v_mfma_f32_16x16x32_bf16 v[64:67], v[84:87], v[8:11], v[64:67]
	ds_read_b128 v[84:87], v232 offset:6144
	s_waitcnt lgkmcnt(1)
	v_mfma_f32_16x16x32_bf16 v[72:75], v[72:75], v[4:7], 0
	s_waitcnt lgkmcnt(0)
	v_mfma_f32_16x16x32_bf16 v[72:75], v[84:87], v[0:3], v[72:75]
	ds_read_b128 v[84:87], v233 offset:6144
	ds_read_b128 v[88:91], v234 offset:6144
	s_waitcnt vmcnt(3)
	ds_write_b128 v227, v[68:71] offset:10240
	s_waitcnt vmcnt(2)
	ds_write_b128 v228, v[160:163] offset:10240
	s_waitcnt vmcnt(1)
	ds_write_b128 v229, v[80:83] offset:10240
	s_waitcnt vmcnt(0)
	ds_write_b128 v230, v[164:167] offset:10240
	ds_read_b128 v[68:71], v231 offset:10240
	ds_read_b128 v[80:83], v232 offset:10240
	s_waitcnt lgkmcnt(7)
	v_mfma_f32_16x16x32_bf16 v[72:75], v[84:87], v[12:15], v[72:75]
	ds_read_b128 v[84:87], v233 offset:10240
	s_waitcnt lgkmcnt(2)
	v_mfma_f32_16x16x32_bf16 v[68:71], v[68:71], v[4:7], 0
	s_waitcnt lgkmcnt(1)
	v_mfma_f32_16x16x32_bf16 v[68:71], v[80:83], v[0:3], v[68:71]
	ds_read_b128 v[80:83], v234 offset:10240
	s_waitcnt lgkmcnt(1)
	v_mfma_f32_16x16x32_bf16 v[68:71], v[84:87], v[12:15], v[68:71]
	v_mfma_f32_16x16x32_bf16 v[72:75], v[88:91], v[8:11], v[72:75]
	s_waitcnt lgkmcnt(0)
	v_mfma_f32_16x16x32_bf16 v[68:71], v[80:83], v[8:11], v[68:71]
	s_and_saveexec_b64 s[2:3], s[0:1]
	s_cbranch_execz .LBB0_2282
	v_readlane_b32 s0, v253, 43
	v_readlane_b32 s1, v253, 45
	s_add_i32 s0, s1, s0
	s_ashr_i32 s1, s0, 31
	s_lshl_b64 s[0:1], s[0:1], 12
	v_lshl_add_u64 v[8:9], v[140:141], 0, s[0:1]
	global_load_dwordx4 v[4:7], v[8:9], off
	global_load_dwordx4 v[0:3], v[8:9], off offset:64
	global_load_dwordx4 v[12:15], v[8:9], off offset:128
	s_nop 0
	global_load_dwordx4 v[8:11], v[8:9], off offset:192
.LBB0_2282:
	s_or_b64 exec, exec, s[2:3]
	s_min_i32 s60, s33, 0xff
	v_mul_f32_e32 v80, 0x3db504f3, v24
	v_max_f32_e32 v80, 0xff61b1e6, v80
	v_cmp_lt_i32_e64 s[26:27], s60, v183
	v_mul_f32_e32 v81, 0x3db504f3, v25
	v_cmp_gt_i32_e64 s[34:35], s60, v183
	v_cndmask_b32_e64 v80, v80, v239, s[26:27]
	v_or_b32_e32 v82, 2, v183
	v_cndmask_b32_e64 v81, v239, v81, s[34:35]
	v_or_b32_e32 v83, 3, v183
	v_max_f32_e32 v80, v80, v81
	v_mul_f32_e32 v81, 0x3db504f3, v26
	v_cmp_lt_i32_e64 s[28:29], s60, v82
	v_mul_f32_e32 v82, 0x3db504f3, v27
	v_cmp_lt_i32_e64 s[30:31], s60, v83
	v_cndmask_b32_e64 v81, v81, v239, s[28:29]
	v_or_b32_e32 v83, 5, v183
	v_cndmask_b32_e64 v82, v82, v239, s[30:31]
	v_max3_f32 v80, v80, v81, v82
	v_or_b32_e32 v82, 4, v183
	v_mul_f32_e32 v81, 0x3db504f3, v40
	v_cmp_lt_i32_e64 s[22:23], s60, v82
	v_mul_f32_e32 v82, 0x3db504f3, v41
	v_cmp_lt_i32_e64 s[24:25], s60, v83
	v_cndmask_b32_e64 v81, v81, v239, s[22:23]
	v_or_b32_e32 v83, 7, v183
	v_cndmask_b32_e64 v82, v82, v239, s[24:25]
	v_max3_f32 v80, v80, v81, v82
	v_or_b32_e32 v82, 6, v183
	v_mul_f32_e32 v81, 0x3db504f3, v42
	v_cmp_lt_i32_e64 s[18:19], s60, v82
	v_mul_f32_e32 v82, 0x3db504f3, v43
	v_cmp_lt_i32_e64 s[20:21], s60, v83
	v_cndmask_b32_e64 v81, v81, v239, s[18:19]
	v_or_b32_e32 v83, 9, v183
	v_cndmask_b32_e64 v82, v82, v239, s[20:21]
	v_max3_f32 v80, v80, v81, v82
	v_or_b32_e32 v82, 8, v183
	v_mul_f32_e32 v81, 0x3db504f3, v44
	v_cmp_lt_i32_e64 s[14:15], s60, v82
	v_mul_f32_e32 v82, 0x3db504f3, v45
	v_cmp_lt_i32_e64 s[16:17], s60, v83
	v_cndmask_b32_e64 v81, v81, v239, s[14:15]
	v_or_b32_e32 v83, 11, v183
	v_cndmask_b32_e64 v82, v82, v239, s[16:17]
	v_max3_f32 v80, v80, v81, v82
	v_or_b32_e32 v82, 10, v183
	v_mul_f32_e32 v81, 0x3db504f3, v46
	v_cmp_lt_i32_e64 s[10:11], s60, v82
	v_mul_f32_e32 v82, 0x3db504f3, v47
	v_cmp_lt_i32_e64 s[12:13], s60, v83
	v_cndmask_b32_e64 v81, v81, v239, s[10:11]
	v_or_b32_e32 v83, 13, v183
	v_cndmask_b32_e64 v82, v82, v239, s[12:13]
	v_max3_f32 v80, v80, v81, v82
	v_or_b32_e32 v82, 12, v183
	v_mul_f32_e32 v81, 0x3db504f3, v76
	v_cmp_lt_i32_e64 s[6:7], s60, v82
	v_mul_f32_e32 v82, 0x3db504f3, v77
	v_cmp_lt_i32_e64 s[8:9], s60, v83
	v_cndmask_b32_e64 v81, v81, v239, s[6:7]
	v_or_b32_e32 v83, 15, v183
	v_cndmask_b32_e64 v82, v82, v239, s[8:9]
	v_max3_f32 v80, v80, v81, v82
	v_or_b32_e32 v82, 14, v183
	v_mul_f32_e32 v81, 0x3db504f3, v78
	v_cmp_lt_i32_e64 s[2:3], s60, v82
	v_mul_f32_e32 v82, 0x3db504f3, v79
	v_cmp_lt_i32_e64 s[4:5], s60, v83
	v_cndmask_b32_e64 v81, v81, v239, s[2:3]
	v_or_b32_e32 v83, 17, v183
	v_cndmask_b32_e64 v82, v82, v239, s[4:5]
	v_max3_f32 v80, v80, v81, v82
	v_or_b32_e32 v82, 16, v183
	v_mul_f32_e32 v81, 0x3db504f3, v28
	v_cmp_lt_i32_e32 vcc, s60, v82
	v_mul_f32_e32 v82, 0x3db504f3, v29
	v_cmp_lt_i32_e64 s[0:1], s60, v83
	v_cndmask_b32_e32 v81, v81, v239, vcc
	v_or_b32_e32 v83, 19, v183
; DI void attn_worker(unsigned char* ws, LAS unsigned char* lds, LAS unsigned* qctr, int wave) {
;     ...
;             for (int e = 0; e < 4; ++e) { const bool ok = (64 * kq + 4 * kt + e) < nvalid; s[kt][e] = ok ? s[kt][e] * 0.08838834764831845f : -3.0e38f; mx = fmaxf(mx, s[kt][e]); }
	v_cndmask_b32_e64 v82, v82, v239, s[0:1]
	v_max3_f32 v80, v80, v81, v82
	v_or_b32_e32 v82, 18, v183
	v_mul_f32_e32 v81, 0x3db504f3, v30
	v_cmp_lt_i32_e64 s[36:37], s60, v82
	v_mul_f32_e32 v82, 0x3db504f3, v31
	v_cmp_lt_i32_e64 s[38:39], s60, v83
	v_cndmask_b32_e64 v81, v81, v239, s[36:37]
	v_cmp_lt_i32_e64 s[56:57], s60, v132
	v_cndmask_b32_e64 v82, v82, v239, s[38:39]
	v_max3_f32 v80, v80, v81, v82
	v_or_b32_e32 v82, 20, v183
	v_mul_f32_e32 v81, 0x3db504f3, v16
	v_cmp_lt_i32_e64 s[96:97], s60, v82
	v_mul_f32_e32 v82, 0x3db504f3, v17
	v_cndmask_b32_e64 v82, v82, v239, s[56:57]
	v_cndmask_b32_e64 v81, v81, v239, s[96:97]
	v_max3_f32 v80, v80, v81, v82
	v_mul_f32_e32 v81, 0x3db504f3, v18
	v_cmp_lt_i32_e64 s[52:53], s60, v185
	v_mul_f32_e32 v82, 0x3db504f3, v19
	v_cmp_lt_i32_e64 s[54:55], s60, v186
	v_cndmask_b32_e64 v81, v81, v239, s[52:53]
	v_cmp_lt_i32_e64 s[48:49], s60, v187
	v_cndmask_b32_e64 v82, v82, v239, s[54:55]
	v_max3_f32 v80, v80, v81, v82
	v_mul_f32_e32 v81, 0x3db504f3, v20
	v_mul_f32_e32 v82, 0x3db504f3, v21
	v_cmp_lt_i32_e64 s[50:51], s60, v188
	v_cndmask_b32_e64 v81, v81, v239, s[48:49]
	v_cmp_lt_i32_e64 s[44:45], s60, v189
	v_cndmask_b32_e64 v82, v82, v239, s[50:51]
	v_max3_f32 v80, v80, v81, v82
	v_mul_f32_e32 v81, 0x3db504f3, v22
	v_mul_f32_e32 v82, 0x3db504f3, v23
	v_cmp_lt_i32_e64 s[46:47], s60, v190
	v_cndmask_b32_e64 v81, v81, v239, s[44:45]
	v_cmp_lt_i32_e64 s[40:41], s60, v191
	v_cndmask_b32_e64 v82, v82, v239, s[46:47]
	v_max3_f32 v80, v80, v81, v82
	v_mul_f32_e32 v81, 0x3db504f3, v36
	v_writelane_b32 v253, s40, 9
	v_mul_f32_e32 v82, 0x3db504f3, v37
	v_cmp_lt_i32_e64 s[42:43], s60, v192
	v_writelane_b32 v253, s41, 10
	v_cndmask_b32_e64 v81, v81, v239, s[40:41]
	v_cndmask_b32_e64 v82, v82, v239, s[42:43]
	v_cmp_lt_i32_e64 s[40:41], s60, v193
	v_max3_f32 v80, v80, v81, v82
	v_mul_f32_e32 v81, 0x3db504f3, v38
	v_writelane_b32 v253, s40, 13
	v_mul_f32_e32 v82, 0x3db504f3, v39
	v_cmp_lt_i32_e64 s[94:95], s60, v208
	v_writelane_b32 v253, s41, 14
	v_cndmask_b32_e64 v81, v81, v239, s[40:41]
	v_cmp_lt_i32_e64 s[40:41], s60, v194
	v_cmp_lt_i32_e64 s[90:91], s60, v209
	v_cmp_lt_i32_e64 s[92:93], s60, v210
	v_writelane_b32 v253, s40, 11
	v_cmp_lt_i32_e64 s[86:87], s60, v211
	v_cmp_lt_i32_e64 s[88:89], s60, v212
	v_writelane_b32 v253, s41, 12
	v_cndmask_b32_e64 v82, v82, v239, s[40:41]
	v_cmp_lt_i32_e64 s[40:41], s60, v195
	v_max3_f32 v80, v80, v81, v82
	v_mul_f32_e32 v81, 0x3db504f3, v32
	v_writelane_b32 v253, s40, 17
	v_mul_f32_e32 v82, 0x3db504f3, v33
	v_cmp_lt_i32_e64 s[82:83], s60, v213
	v_writelane_b32 v253, s41, 18
	v_cndmask_b32_e64 v81, v81, v239, s[40:41]
	v_cmp_lt_i32_e64 s[40:41], s60, v196
	v_cmp_lt_i32_e64 s[84:85], s60, v214
	v_cmp_lt_i32_e64 s[80:81], s60, v216
	v_writelane_b32 v253, s40, 15
	v_cmp_lt_i32_e64 s[74:75], s60, v217
	v_cmp_lt_i32_e64 s[76:77], s60, v218
	v_writelane_b32 v253, s41, 16
	v_cndmask_b32_e64 v82, v82, v239, s[40:41]
	v_cmp_lt_i32_e64 s[40:41], s60, v197
	v_max3_f32 v80, v80, v81, v82
	v_mul_f32_e32 v81, 0x3db504f3, v34
	v_writelane_b32 v253, s40, 21
	v_mul_f32_e32 v82, 0x3db504f3, v35
	v_cmp_lt_i32_e64 s[70:71], s60, v219
	v_writelane_b32 v253, s41, 22
	v_cndmask_b32_e64 v81, v81, v239, s[40:41]
	v_cmp_lt_i32_e64 s[40:41], s60, v198
	v_cmp_lt_i32_e64 s[72:73], s60, v220
	v_and_b32_e32 v84, 64, v235
	v_writelane_b32 v253, s40, 19
	v_cmp_lt_i32_e64 s[66:67], s60, v221
	v_cmp_lt_i32_e64 s[68:69], s60, v222
	v_writelane_b32 v253, s41, 20
	v_cndmask_b32_e64 v82, v82, v239, s[40:41]
	v_cmp_lt_i32_e64 s[40:41], s60, v199
	v_max3_f32 v80, v80, v81, v82
	v_mul_f32_e32 v81, 0x3db504f3, v60
	v_writelane_b32 v253, s40, 25
	v_mul_f32_e32 v82, 0x3db504f3, v61
	v_xor_b32_e32 v83, 16, v235
	v_writelane_b32 v253, s41, 26
	v_cndmask_b32_e64 v81, v81, v239, s[40:41]
	v_cmp_lt_i32_e64 s[40:41], s60, v200
	v_add_u32_e32 v84, 64, v84
	v_cmp_lt_i32_e64 s[58:59], v83, v84
	v_writelane_b32 v253, s40, 23
	v_xor_b32_e32 v85, 32, v235
	v_cmp_lt_i32_e64 s[62:63], s60, v223
	v_writelane_b32 v253, s41, 24
	v_cndmask_b32_e64 v82, v82, v239, s[40:41]
	v_cmp_lt_i32_e64 s[40:41], s60, v201
	v_max3_f32 v80, v80, v81, v82
	v_mul_f32_e32 v81, 0x3db504f3, v62
	v_writelane_b32 v253, s40, 29
	v_mul_f32_e32 v82, 0x3db504f3, v63
	v_cmp_lt_i32_e64 s[64:65], s60, v224
	v_writelane_b32 v253, s41, 30
	v_cndmask_b32_e64 v81, v81, v239, s[40:41]
	v_cmp_lt_i32_e64 s[40:41], s60, v202
	v_cndmask_b32_e64 v83, v235, v83, s[58:59]
	v_cmp_lt_i32_e64 s[58:59], v85, v84
	v_writelane_b32 v253, s40, 27
	v_lshlrev_b32_e32 v241, 2, v83
	v_cndmask_b32_e64 v84, v235, v85, s[58:59]
	v_writelane_b32 v253, s41, 28
	v_cndmask_b32_e64 v82, v82, v239, s[40:41]
	v_cmp_lt_i32_e64 s[40:41], s60, v203
	v_max3_f32 v80, v80, v81, v82
	v_mul_f32_e32 v81, 0x3db504f3, v52
	v_writelane_b32 v253, s40, 33
	v_mul_f32_e32 v82, 0x3db504f3, v53
	v_cmp_lt_i32_e64 s[58:59], s60, v225
	v_writelane_b32 v253, s41, 34
	v_cndmask_b32_e64 v81, v81, v239, s[40:41]
	v_cmp_lt_i32_e64 s[40:41], s60, v204
	v_lshlrev_b32_e32 v240, 2, v84
	s_nop 0
	v_writelane_b32 v253, s40, 31
	s_nop 1
	v_writelane_b32 v253, s41, 32
	v_cndmask_b32_e64 v82, v82, v239, s[40:41]
	v_cmp_lt_i32_e64 s[40:41], s60, v205
	v_max3_f32 v80, v80, v81, v82
	v_mul_f32_e32 v81, 0x3db504f3, v54
	v_writelane_b32 v253, s40, 37
	v_mul_f32_e32 v82, 0x3db504f3, v55
	s_nop 0
	v_writelane_b32 v253, s41, 38
	v_cndmask_b32_e64 v81, v81, v239, s[40:41]
	v_cmp_lt_i32_e64 s[40:41], s60, v206
	s_nop 1
	v_writelane_b32 v253, s40, 35
	s_nop 1
	v_cndmask_b32_e64 v82, v82, v239, s[40:41]
	v_writelane_b32 v253, s41, 36
	v_max3_f32 v80, v80, v81, v82
	v_mul_f32_e32 v81, 0x3db504f3, v48
	v_cmp_lt_i32_e64 s[40:41], s60, v207
; DI void attn_worker(unsigned char* ws, LAS unsigned char* lds, LAS unsigned* qctr, int wave) {
;     ...
;             for (int e = 0; e < 4; ++e) { const bool ok = (64 * kq + 4 * kt + e) < nvalid; s[kt][e] = ok ? s[kt][e] * 0.08838834764831845f : -3.0e38f; mx = fmaxf(mx, s[kt][e]); }
;         mx = fmaxf(mx, __shfl_xor(mx, 16)); mx = fmaxf(mx, __shfl_xor(mx, 32));
;         float sum = 0.f;
; #pragma unroll
;         for (int kt = 0; kt < 16; ++kt)
; #pragma unroll
;             for (int e = 0; e < 4; ++e) { const bool ok = (64 * kq + 4 * kt + e) < nvalid; const float p = ok ? __expf(s[kt][e] - mx) : 0.f; s[kt][e] = p; sum += p; }
	v_mul_f32_e32 v82, 0x3db504f3, v49
	v_cndmask_b32_e64 v82, v82, v239, s[94:95]
	v_writelane_b32 v253, s40, 39
	s_nop 1
	v_cndmask_b32_e64 v81, v81, v239, s[40:41]
	v_max3_f32 v80, v80, v81, v82
	v_mul_f32_e32 v81, 0x3db504f3, v50
	v_mul_f32_e32 v82, 0x3db504f3, v51
	v_cndmask_b32_e64 v81, v81, v239, s[90:91]
	v_cndmask_b32_e64 v82, v82, v239, s[92:93]
	v_max3_f32 v80, v80, v81, v82
	v_mul_f32_e32 v81, 0x3db504f3, v56
	v_mul_f32_e32 v82, 0x3db504f3, v57
	v_cndmask_b32_e64 v81, v81, v239, s[86:87]
	v_cndmask_b32_e64 v82, v82, v239, s[88:89]
	v_max3_f32 v80, v80, v81, v82
	v_mul_f32_e32 v81, 0x3db504f3, v58
	v_mul_f32_e32 v82, 0x3db504f3, v59
	v_cndmask_b32_e64 v81, v81, v239, s[82:83]
	v_cndmask_b32_e64 v82, v82, v239, s[84:85]
	v_writelane_b32 v253, s41, 40
	v_max3_f32 v80, v80, v81, v82
	v_mul_f32_e32 v81, 0x3db504f3, v64
	v_cmp_lt_i32_e64 s[40:41], s60, v215
	v_mul_f32_e32 v82, 0x3db504f3, v65
	v_cndmask_b32_e64 v82, v82, v239, s[80:81]
	v_cndmask_b32_e64 v81, v81, v239, s[40:41]
	v_max3_f32 v80, v80, v81, v82
	v_mul_f32_e32 v81, 0x3db504f3, v66
	v_mul_f32_e32 v82, 0x3db504f3, v67
	v_cndmask_b32_e64 v81, v81, v239, s[74:75]
	v_cndmask_b32_e64 v82, v82, v239, s[76:77]
	v_max3_f32 v80, v80, v81, v82
	v_mul_f32_e32 v81, 0x3db504f3, v72
	v_mul_f32_e32 v82, 0x3db504f3, v73
	v_cndmask_b32_e64 v81, v81, v239, s[70:71]
	v_cndmask_b32_e64 v82, v82, v239, s[72:73]
	v_max3_f32 v80, v80, v81, v82
	v_mul_f32_e32 v81, 0x3db504f3, v74
	v_mul_f32_e32 v82, 0x3db504f3, v75
	v_cndmask_b32_e64 v81, v81, v239, s[66:67]
	v_cndmask_b32_e64 v82, v82, v239, s[68:69]
	v_max3_f32 v80, v80, v81, v82
	v_mul_f32_e32 v81, 0x3db504f3, v68
	v_mul_f32_e32 v82, 0x3db504f3, v69
	v_cndmask_b32_e64 v81, v81, v239, s[62:63]
	v_cndmask_b32_e64 v82, v82, v239, s[64:65]
	v_max3_f32 v80, v80, v81, v82
	v_mul_f32_e32 v81, 0x3db504f3, v70
	v_mul_f32_e32 v82, 0x3db504f3, v71
	v_cmp_lt_i32_e64 s[60:61], s60, v226
	v_cndmask_b32_e64 v81, v81, v239, s[58:59]
	s_nop 0
	v_cndmask_b32_e64 v82, v82, v239, s[60:61]
	v_max3_f32 v80, v80, v81, v82
	ds_bpermute_b32 v81, v241, v80
	s_waitcnt lgkmcnt(0)
	v_max_f32_e32 v81, v81, v81
	v_max_f32_e32 v80, v80, v81
	ds_bpermute_b32 v81, v240, v80
	s_waitcnt lgkmcnt(0)
	v_max_f32_e32 v81, v81, v81
	v_max_f32_e32 v242, v80, v81
	v_fma_f32 v24, v24, s78, -v242
	v_mul_f32_e32 v24, 0x3fb8aa3b, v24
	v_exp_f32_e32 v24, v24
	v_fma_f32 v30, v30, s78, -v242
	v_mul_f32_e32 v30, 0x3fb8aa3b, v30
	v_fma_f32 v31, v31, s78, -v242
	v_cndmask_b32_e64 v124, v24, 0, s[26:27]
	v_fma_f32 v24, v25, s78, -v242
	v_mul_f32_e32 v24, 0x3fb8aa3b, v24
	v_exp_f32_e32 v24, v24
	v_exp_f32_e32 v30, v30
	v_mul_f32_e32 v31, 0x3fb8aa3b, v31
	v_fma_f32 v16, v16, s78, -v242
	v_cndmask_b32_e64 v125, 0, v24, s[34:35]
	v_fma_f32 v24, v26, s78, -v242
	v_mul_f32_e32 v24, 0x3fb8aa3b, v24
	v_exp_f32_e32 v24, v24
	v_exp_f32_e32 v31, v31
	v_mul_f32_e32 v16, 0x3fb8aa3b, v16
	v_fma_f32 v17, v17, s78, -v242
	v_cndmask_b32_e64 v128, v24, 0, s[28:29]
	v_fma_f32 v24, v27, s78, -v242
	v_mul_f32_e32 v24, 0x3fb8aa3b, v24
	v_exp_f32_e32 v24, v24
	v_exp_f32_e32 v16, v16
	v_mul_f32_e32 v17, 0x3fb8aa3b, v17
	v_fma_f32 v18, v18, s78, -v242
	v_cndmask_b32_e64 v129, v24, 0, s[30:31]
	v_fma_f32 v24, v40, s78, -v242
	v_mul_f32_e32 v24, 0x3fb8aa3b, v24
	v_exp_f32_e32 v24, v24
	v_exp_f32_e32 v17, v17
	v_mul_f32_e32 v18, 0x3fb8aa3b, v18
	v_fma_f32 v19, v19, s78, -v242
	v_cndmask_b32_e64 v130, v24, 0, s[22:23]
	v_fma_f32 v24, v41, s78, -v242
	v_mul_f32_e32 v24, 0x3fb8aa3b, v24
	v_exp_f32_e32 v24, v24
	v_cndmask_b32_e64 v30, v30, 0, s[36:37]
	v_exp_f32_e32 v18, v18
	v_mul_f32_e32 v19, 0x3fb8aa3b, v19
	v_cndmask_b32_e64 v131, v24, 0, s[24:25]
	v_fma_f32 v24, v42, s78, -v242
	v_mul_f32_e32 v24, 0x3fb8aa3b, v24
	v_exp_f32_e32 v24, v24
	v_cndmask_b32_e64 v31, v31, 0, s[38:39]
	v_exp_f32_e32 v19, v19
	v_cndmask_b32_e64 v16, v16, 0, s[96:97]
	v_cndmask_b32_e64 v148, v24, 0, s[18:19]
	v_fma_f32 v24, v43, s78, -v242
	v_mul_f32_e32 v24, 0x3fb8aa3b, v24
	v_exp_f32_e32 v24, v24
	v_cndmask_b32_e64 v17, v17, 0, s[56:57]
	v_fma_f32 v32, v32, s78, -v242
	v_mul_f32_e32 v32, 0x3fb8aa3b, v32
	v_cndmask_b32_e64 v149, v24, 0, s[20:21]
	v_fma_f32 v24, v44, s78, -v242
	v_mul_f32_e32 v24, 0x3fb8aa3b, v24
	v_exp_f32_e32 v24, v24
	v_exp_f32_e32 v32, v32
	v_fma_f32 v33, v33, s78, -v242
	v_mul_f32_e32 v33, 0x3fb8aa3b, v33
	v_cndmask_b32_e64 v126, v24, 0, s[14:15]
	v_fma_f32 v24, v45, s78, -v242
	v_mul_f32_e32 v24, 0x3fb8aa3b, v24
	v_exp_f32_e32 v24, v24
	v_exp_f32_e32 v33, v33
	v_fma_f32 v34, v34, s78, -v242
	v_mul_f32_e32 v34, 0x3fb8aa3b, v34
	v_cndmask_b32_e64 v127, v24, 0, s[16:17]
	v_fma_f32 v24, v46, s78, -v242
	v_mul_f32_e32 v24, 0x3fb8aa3b, v24
	v_exp_f32_e32 v24, v24
	v_exp_f32_e32 v34, v34
	v_fma_f32 v35, v35, s78, -v242
	v_mul_f32_e32 v35, 0x3fb8aa3b, v35
	v_cndmask_b32_e64 v144, v24, 0, s[10:11]
	v_fma_f32 v24, v47, s78, -v242
	v_mul_f32_e32 v24, 0x3fb8aa3b, v24
	v_exp_f32_e32 v24, v24
	v_exp_f32_e32 v35, v35
	v_cndmask_b32_e64 v145, v24, 0, s[12:13]
	v_fma_f32 v24, v76, s78, -v242
	v_mul_f32_e32 v24, 0x3fb8aa3b, v24
	v_exp_f32_e32 v24, v24
	s_nop 0
	v_cndmask_b32_e64 v146, v24, 0, s[6:7]
	v_fma_f32 v24, v77, s78, -v242
	v_mul_f32_e32 v24, 0x3fb8aa3b, v24
	v_exp_f32_e32 v24, v24
	s_nop 0
	v_cndmask_b32_e64 v147, v24, 0, s[8:9]
	v_fma_f32 v24, v78, s78, -v242
	v_mul_f32_e32 v24, 0x3fb8aa3b, v24
	v_exp_f32_e32 v24, v24
	s_nop 0
	v_cndmask_b32_e64 v150, v24, 0, s[2:3]
	v_fma_f32 v24, v79, s78, -v242
	v_mul_f32_e32 v24, 0x3fb8aa3b, v24
	v_exp_f32_e32 v24, v24
	s_nop 0
	v_cndmask_b32_e64 v151, v24, 0, s[4:5]
	v_fma_f32 v24, v28, s78, -v242
	v_mul_f32_e32 v24, 0x3fb8aa3b, v24
	v_exp_f32_e32 v24, v24
	s_nop 0
	v_cndmask_b32_e64 v28, v24, 0, vcc
	v_fma_f32 v24, v29, s78, -v242
	v_mul_f32_e32 v24, 0x3fb8aa3b, v24
	v_exp_f32_e32 v24, v24
	s_nop 0
	v_cndmask_b32_e64 v29, v24, 0, s[0:1]
	ds_read_b128 v[24:27], v182
	ds_read_b128 v[40:43], v182 offset:16
	v_readlane_b32 s0, v253, 9
	v_readlane_b32 s1, v253, 10
	s_waitcnt lgkmcnt(1)
; #define LAS __attribute__((address_space(3)))
; #define ATT_FENCE() asm volatile("" ::: "memory")
; DI void attn_worker(unsigned char* ws, LAS unsigned char* lds, LAS unsigned* qctr, int wave) {
;     ...
;         v4i ix[3][2]; v4u vv[3][8];
; #pragma unroll
;         for (int ch = 0; ch < 2; ++ch) {
;             ix[ch][0] = *(const LAS v4i*)(idl + 64 * kg + 8 * ch); ix[ch][1] = *(const LAS v4i*)(idl + 64 * kg + 8 * ch + 4);
; #pragma unroll
;             for (int j = 0; j < 8; ++j) vv[ch][j] = *(const v4u*)(vbase + (size_t)ix[ch][j >> 2][j & 3] * KVD);
;             ATT_FENCE(); }
;     ...
;         float sum = 0.f;
; #pragma unroll
;         for (int kt = 0; kt < 16; ++kt)
; #pragma unroll
;             for (int e = 0; e < 4; ++e) { const bool ok = (64 * kq + 4 * kt + e) < nvalid; const float p = ok ? __expf(s[kt][e] - mx) : 0.f; s[kt][e] = p; sum += p; }
	v_lshl_add_u32 v44, v24, 10, v252
	v_lshl_add_u32 v46, v25, 10, v252
	global_load_dwordx4 v[88:91], v44, s[100:101]
	global_load_dwordx4 v[92:95], v46, s[100:101]
	v_lshl_add_u32 v24, v26, 10, v252
	v_lshl_add_u32 v44, v27, 10, v252
	global_load_dwordx4 v[96:99], v24, s[100:101]
	global_load_dwordx4 v[100:103], v44, s[100:101]
	s_waitcnt lgkmcnt(0)
	v_lshl_add_u32 v24, v40, 10, v252
	v_lshl_add_u32 v26, v41, 10, v252
	global_load_dwordx4 v[104:107], v24, s[100:101]
	global_load_dwordx4 v[108:111], v26, s[100:101]
	v_lshl_add_u32 v24, v42, 10, v252
	v_lshl_add_u32 v26, v43, 10, v252
	global_load_dwordx4 v[112:115], v24, s[100:101]
	global_load_dwordx4 v[116:119], v26, s[100:101]
	ds_read_b128 v[42:45], v182 offset:32
	ds_read_b128 v[120:123], v182 offset:48
	s_waitcnt lgkmcnt(1)
	s_waitcnt lgkmcnt(0)
	v_lshl_add_u32 v80, v120, 10, v252
	v_add_f32_e32 v120, 0, v124
	v_add_f32_e32 v120, v125, v120
	v_add_f32_e32 v120, v128, v120
	v_add_f32_e32 v120, v129, v120
	v_add_f32_e32 v120, v130, v120
	v_add_f32_e32 v120, v131, v120
	v_add_f32_e32 v120, v148, v120
	v_add_f32_e32 v120, v149, v120
	v_add_f32_e32 v120, v126, v120
	v_add_f32_e32 v120, v127, v120
	v_add_f32_e32 v120, v144, v120
	v_add_f32_e32 v120, v145, v120
	v_add_f32_e32 v120, v146, v120
	v_add_f32_e32 v120, v147, v120
	v_add_f32_e32 v120, v150, v120
	v_add_f32_e32 v120, v151, v120
	v_add_f32_e32 v120, v28, v120
	v_add_f32_e32 v120, v29, v120
	v_add_f32_e32 v120, v30, v120
	v_add_f32_e32 v120, v31, v120
	v_add_f32_e32 v120, v16, v120
	v_lshl_add_u32 v82, v121, 10, v252
	v_add_f32_e32 v121, v17, v120
	v_cndmask_b32_e64 v120, v18, 0, s[52:53]
	v_add_f32_e32 v18, v120, v121
	v_cndmask_b32_e64 v121, v19, 0, s[54:55]
	v_fma_f32 v19, v20, s78, -v242
	v_fma_f32 v20, v21, s78, -v242
	v_mul_f32_e32 v19, 0x3fb8aa3b, v19
	v_mul_f32_e32 v20, 0x3fb8aa3b, v20
	v_exp_f32_e32 v19, v19
	v_exp_f32_e32 v20, v20
	v_add_f32_e32 v21, v121, v18
	v_lshl_add_u32 v24, v42, 10, v252
	v_cndmask_b32_e64 v18, v19, 0, s[48:49]
	v_cndmask_b32_e64 v19, v20, 0, s[50:51]
	v_fma_f32 v20, v22, s78, -v242
	v_mul_f32_e32 v20, 0x3fb8aa3b, v20
	v_fma_f32 v22, v23, s78, -v242
	v_exp_f32_e32 v20, v20
	v_mul_f32_e32 v22, 0x3fb8aa3b, v22
	v_exp_f32_e32 v22, v22
	v_add_f32_e32 v21, v18, v21
	v_add_f32_e32 v21, v19, v21
	v_cndmask_b32_e64 v20, v20, 0, s[44:45]
	v_add_f32_e32 v23, v20, v21
	v_cndmask_b32_e64 v21, v22, 0, s[46:47]
	v_fma_f32 v22, v36, s78, -v242
	v_mul_f32_e32 v22, 0x3fb8aa3b, v22
	v_fma_f32 v36, v37, s78, -v242
	v_exp_f32_e32 v22, v22
	v_mul_f32_e32 v36, 0x3fb8aa3b, v36
	v_exp_f32_e32 v36, v36
	v_add_f32_e32 v23, v21, v23
	v_cndmask_b32_e64 v22, v22, 0, s[0:1]
	v_add_f32_e32 v37, v22, v23
	v_cndmask_b32_e64 v23, v36, 0, s[42:43]
	v_fma_f32 v36, v38, s78, -v242
	v_mul_f32_e32 v36, 0x3fb8aa3b, v36
	v_exp_f32_e32 v36, v36
	v_fma_f32 v38, v39, s78, -v242
	v_mul_f32_e32 v38, 0x3fb8aa3b, v38
	v_exp_f32_e32 v38, v38
	v_readlane_b32 s0, v253, 13
	v_readlane_b32 s1, v253, 14
	v_add_f32_e32 v37, v23, v37
	s_nop 0
	v_cndmask_b32_e64 v36, v36, 0, s[0:1]
	v_readlane_b32 s0, v253, 11
	v_readlane_b32 s1, v253, 12
	v_add_f32_e32 v39, v36, v37
	v_lshl_add_u32 v26, v43, 10, v252
	v_cndmask_b32_e64 v37, v38, 0, s[0:1]
	v_readlane_b32 s0, v253, 17
	v_readlane_b32 s1, v253, 18
	v_add_f32_e32 v38, v37, v39
	v_fma_f32 v39, v60, s78, -v242
	v_cndmask_b32_e64 v32, v32, 0, s[0:1]
	v_readlane_b32 s0, v253, 15
	v_readlane_b32 s1, v253, 16
	v_mul_f32_e32 v39, 0x3fb8aa3b, v39
	v_exp_f32_e32 v39, v39
	v_cndmask_b32_e64 v33, v33, 0, s[0:1]
	v_readlane_b32 s0, v253, 21
	v_readlane_b32 s1, v253, 22
	v_fma_f32 v60, v61, s78, -v242
	v_mul_f32_e32 v60, 0x3fb8aa3b, v60
	v_cndmask_b32_e64 v34, v34, 0, s[0:1]
	v_readlane_b32 s0, v253, 19
	v_readlane_b32 s1, v253, 20
	v_exp_f32_e32 v60, v60
	v_add_f32_e32 v38, v32, v38
	v_cndmask_b32_e64 v35, v35, 0, s[0:1]
	v_readlane_b32 s0, v253, 25
	v_readlane_b32 s1, v253, 26
	v_add_f32_e32 v38, v33, v38
	v_add_f32_e32 v38, v34, v38
	v_cndmask_b32_e64 v152, v39, 0, s[0:1]
	v_fma_f32 v39, v62, s78, -v242
	v_mul_f32_e32 v39, 0x3fb8aa3b, v39
	v_readlane_b32 s0, v253, 23
	v_exp_f32_e32 v39, v39
	v_readlane_b32 s1, v253, 24
	v_add_f32_e32 v38, v35, v38
	v_add_f32_e32 v38, v152, v38
	v_cndmask_b32_e64 v153, v60, 0, s[0:1]
	v_fma_f32 v60, v63, s78, -v242
	v_readlane_b32 s0, v253, 29
	v_mul_f32_e32 v60, 0x3fb8aa3b, v60
	v_readlane_b32 s1, v253, 30
	v_exp_f32_e32 v60, v60
	v_add_f32_e32 v38, v153, v38
	v_cndmask_b32_e64 v156, v39, 0, s[0:1]
	v_fma_f32 v39, v52, s78, -v242
	v_mul_f32_e32 v39, 0x3fb8aa3b, v39
	v_readlane_b32 s0, v253, 27
	v_exp_f32_e32 v39, v39
	v_readlane_b32 s1, v253, 28
	v_fma_f32 v52, v53, s78, -v242
	v_mul_f32_e32 v52, 0x3fb8aa3b, v52
	v_cndmask_b32_e64 v157, v60, 0, s[0:1]
	v_readlane_b32 s0, v253, 33
	v_readlane_b32 s1, v253, 34
	v_exp_f32_e32 v52, v52
	v_add_f32_e32 v38, v156, v38
	v_cndmask_b32_e64 v154, v39, 0, s[0:1]
	v_fma_f32 v39, v54, s78, -v242
	v_mul_f32_e32 v39, 0x3fb8aa3b, v39
	v_readlane_b32 s0, v253, 31
	v_exp_f32_e32 v39, v39
	v_readlane_b32 s1, v253, 32
	v_add_f32_e32 v38, v157, v38
	v_add_f32_e32 v38, v154, v38
	v_cndmask_b32_e64 v155, v52, 0, s[0:1]
	v_fma_f32 v52, v55, s78, -v242
	v_readlane_b32 s0, v253, 37
	v_mul_f32_e32 v52, 0x3fb8aa3b, v52
	v_readlane_b32 s1, v253, 38
	v_exp_f32_e32 v52, v52
	v_add_f32_e32 v38, v155, v38
	v_cndmask_b32_e64 v158, v39, 0, s[0:1]
	v_fma_f32 v39, v48, s78, -v242
	v_mul_f32_e32 v39, 0x3fb8aa3b, v39
	v_fma_f32 v48, v49, s78, -v242
	v_readlane_b32 s0, v253, 35
	v_exp_f32_e32 v39, v39
	v_mul_f32_e32 v48, 0x3fb8aa3b, v48
	v_readlane_b32 s1, v253, 36
	v_exp_f32_e32 v48, v48
	v_add_f32_e32 v38, v158, v38
	v_cndmask_b32_e64 v159, v52, 0, s[0:1]
; #define LAS __attribute__((address_space(3)))
; DI v4u pack8(const f4& a, const f4& b) { v4u w; w.x = cvt_pk_bf16(a[0], a[1]); w.y = cvt_pk_bf16(a[2], a[3]); w.z = cvt_pk_bf16(b[0], b[1]); w.w = cvt_pk_bf16(b[2], b[3]); return w; }
; #define ATT_FENCE() asm volatile("" ::: "memory")
; DI void attn_worker(unsigned char* ws, LAS unsigned char* lds, LAS unsigned* qctr, int wave) {
;     ...
;         for (int ch = 0; ch < 2; ++ch) {
;             ix[ch][0] = *(const LAS v4i*)(idl + 64 * kg + 8 * ch); ix[ch][1] = *(const LAS v4i*)(idl + 64 * kg + 8 * ch + 4);
; #pragma unroll
;             for (int j = 0; j < 8; ++j) vv[ch][j] = *(const v4u*)(vbase + (size_t)ix[ch][j >> 2][j & 3] * KVD);
;             ATT_FENCE(); }
;     ...
;         float sum = 0.f;
; #pragma unroll
;         for (int kt = 0; kt < 16; ++kt)
; #pragma unroll
;             for (int e = 0; e < 4; ++e) { const bool ok = (64 * kq + 4 * kt + e) < nvalid; const float p = ok ? __expf(s[kt][e] - mx) : 0.f; s[kt][e] = p; sum += p; }
;         sum += __shfl_xor(sum, 16); sum += __shfl_xor(sum, 32);
;         const float inv = 1.0f / sum;
;         bf16x8 pa[8];
; #pragma unroll
;         for (int sg = 0; sg < 8; ++sg) pa[sg] = __builtin_bit_cast(bf16x8, epi::pack8(s[2 * sg] * inv, s[2 * sg + 1] * inv));
	v_readlane_b32 s0, v253, 39
	v_readlane_b32 s1, v253, 40
	v_cndmask_b32_e64 v161, v48, 0, s[94:95]
	v_fma_f32 v48, v51, s78, -v242
	v_cndmask_b32_e64 v160, v39, 0, s[0:1]
	v_fma_f32 v39, v50, s78, -v242
	v_mul_f32_e32 v39, 0x3fb8aa3b, v39
	v_exp_f32_e32 v39, v39
	v_mul_f32_e32 v48, 0x3fb8aa3b, v48
	v_exp_f32_e32 v48, v48
	v_add_f32_e32 v38, v159, v38
	v_cndmask_b32_e64 v164, v39, 0, s[90:91]
	v_fma_f32 v39, v56, s78, -v242
	v_cndmask_b32_e64 v165, v48, 0, s[92:93]
	v_mul_f32_e32 v39, 0x3fb8aa3b, v39
	v_fma_f32 v48, v57, s78, -v242
	v_exp_f32_e32 v39, v39
	v_mul_f32_e32 v48, 0x3fb8aa3b, v48
	v_exp_f32_e32 v48, v48
	v_add_f32_e32 v38, v160, v38
	v_cndmask_b32_e64 v162, v39, 0, s[86:87]
	v_fma_f32 v39, v58, s78, -v242
	v_cndmask_b32_e64 v163, v48, 0, s[88:89]
	v_mul_f32_e32 v39, 0x3fb8aa3b, v39
	v_fma_f32 v48, v59, s78, -v242
	v_exp_f32_e32 v39, v39
	v_mul_f32_e32 v48, 0x3fb8aa3b, v48
	v_exp_f32_e32 v48, v48
	v_add_f32_e32 v38, v161, v38
	v_cndmask_b32_e64 v166, v39, 0, s[82:83]
	v_fma_f32 v39, v64, s78, -v242
	v_cndmask_b32_e64 v167, v48, 0, s[84:85]
	v_mul_f32_e32 v39, 0x3fb8aa3b, v39
	v_fma_f32 v48, v65, s78, -v242
	v_exp_f32_e32 v39, v39
	v_mul_f32_e32 v48, 0x3fb8aa3b, v48
	v_exp_f32_e32 v48, v48
	v_add_f32_e32 v38, v164, v38
	v_cndmask_b32_e64 v168, v39, 0, s[40:41]
	v_fma_f32 v39, v66, s78, -v242
	v_cndmask_b32_e64 v169, v48, 0, s[80:81]
	v_mul_f32_e32 v39, 0x3fb8aa3b, v39
	v_fma_f32 v48, v67, s78, -v242
	v_exp_f32_e32 v39, v39
	v_mul_f32_e32 v48, 0x3fb8aa3b, v48
	v_exp_f32_e32 v48, v48
	v_add_f32_e32 v38, v165, v38
	v_cndmask_b32_e64 v170, v39, 0, s[74:75]
	v_fma_f32 v39, v72, s78, -v242
	v_cndmask_b32_e64 v171, v48, 0, s[76:77]
	v_mul_f32_e32 v39, 0x3fb8aa3b, v39
	v_fma_f32 v48, v73, s78, -v242
	v_exp_f32_e32 v39, v39
	v_mul_f32_e32 v48, 0x3fb8aa3b, v48
	v_exp_f32_e32 v48, v48
	v_add_f32_e32 v38, v162, v38
	v_cndmask_b32_e64 v72, v39, 0, s[70:71]
	v_fma_f32 v39, v74, s78, -v242
	v_cndmask_b32_e64 v73, v48, 0, s[72:73]
	v_mul_f32_e32 v39, 0x3fb8aa3b, v39
	v_fma_f32 v48, v75, s78, -v242
	v_exp_f32_e32 v39, v39
	v_mul_f32_e32 v48, 0x3fb8aa3b, v48
	v_exp_f32_e32 v48, v48
	v_add_f32_e32 v38, v163, v38
	v_cndmask_b32_e64 v74, v39, 0, s[66:67]
	v_fma_f32 v39, v68, s78, -v242
	v_add_f32_e32 v38, v166, v38
	v_cndmask_b32_e64 v75, v48, 0, s[68:69]
	v_mul_f32_e32 v39, 0x3fb8aa3b, v39
	v_fma_f32 v48, v69, s78, -v242
	v_add_f32_e32 v38, v167, v38
	v_exp_f32_e32 v39, v39
	v_mul_f32_e32 v48, 0x3fb8aa3b, v48
	v_add_f32_e32 v38, v168, v38
	v_exp_f32_e32 v48, v48
	v_add_f32_e32 v38, v169, v38
	v_add_f32_e32 v38, v170, v38
	v_add_f32_e32 v38, v171, v38
	v_cndmask_b32_e64 v68, v39, 0, s[62:63]
	v_fma_f32 v39, v70, s78, -v242
	v_add_f32_e32 v38, v72, v38
	v_cndmask_b32_e64 v69, v48, 0, s[64:65]
	v_mul_f32_e32 v39, 0x3fb8aa3b, v39
	v_fma_f32 v48, v71, s78, -v242
	v_add_f32_e32 v38, v73, v38
	v_exp_f32_e32 v39, v39
	v_mul_f32_e32 v48, 0x3fb8aa3b, v48
	v_add_f32_e32 v38, v74, v38
	v_exp_f32_e32 v48, v48
	v_add_f32_e32 v38, v75, v38
	v_add_f32_e32 v38, v68, v38
	v_add_f32_e32 v38, v69, v38
	v_cndmask_b32_e64 v70, v39, 0, s[58:59]
	v_add_f32_e32 v38, v70, v38
	v_cndmask_b32_e64 v71, v48, 0, s[60:61]
	v_add_f32_e32 v48, v71, v38
	ds_bpermute_b32 v49, v241, v48
	v_lshl_add_u32 v46, v44, 10, v252
	v_lshl_add_u32 v76, v45, 10, v252
	v_lshl_add_u32 v38, v122, 10, v252
	s_waitcnt lgkmcnt(0)
	v_add_f32_e32 v50, v48, v49
	v_lshl_add_u32 v48, v123, 10, v252
	v_mov_b32_e32 v40, v26
	v_mov_b32_e32 v84, v82
	global_load_dwordx4 v[24:27], v24, s[100:101]
	s_nop 0
	global_load_dwordx4 v[40:43], v40, s[100:101]
	s_nop 0
	global_load_dwordx4 v[44:47], v46, s[100:101]
	s_nop 0
	global_load_dwordx4 v[76:79], v76, s[100:101]
	s_nop 0
	global_load_dwordx4 v[80:83], v80, s[100:101]
	s_nop 0
	global_load_dwordx4 v[84:87], v84, s[100:101]
	global_load_dwordx4 v[52:55], v38, s[100:101]
	global_load_dwordx4 v[56:59], v48, s[100:101]
	ds_bpermute_b32 v51, v240, v50
	s_waitcnt lgkmcnt(0)
	v_add_f32_e32 v50, v50, v51
	v_div_scale_f32 v51, s[0:1], v50, v50, 1.0
	v_rcp_f32_e32 v60, v51
	s_nop 0
	v_fma_f32 v38, -v51, v60, 1.0
	v_fmac_f32_e32 v60, v38, v60
	v_div_scale_f32 v38, vcc, 1.0, v50, 1.0
	v_mul_f32_e32 v39, v38, v60
	v_fma_f32 v48, -v51, v39, v38
	v_fmac_f32_e32 v39, v48, v60
	v_fma_f32 v38, -v51, v39, v38
	v_div_fmas_f32 v38, v38, v60, v39
	v_div_fixup_f32 v122, v38, v50, 1.0
	v_pk_mul_f32 v[48:49], v[124:125], v[122:123] op_sel_hi:[1,0]
	v_pk_mul_f32 v[50:51], v[148:149], v[122:123] op_sel_hi:[1,0]
	v_pk_mul_f32 v[38:39], v[128:129], v[122:123] op_sel_hi:[1,0]
	v_pk_mul_f32 v[60:61], v[130:131], v[122:123] op_sel_hi:[1,0]
	v_cvt_pk_bf16_f32 v64, v48, v49
	v_cvt_pk_bf16_f32 v65, v38, v39
	v_pk_mul_f32 v[48:49], v[126:127], v[122:123] op_sel_hi:[1,0]
	v_cvt_pk_bf16_f32 v66, v60, v61
	v_cvt_pk_bf16_f32 v67, v50, v51
	v_pk_mul_f32 v[50:51], v[150:151], v[122:123] op_sel_hi:[1,0]
	v_pk_mul_f32 v[62:63], v[146:147], v[122:123] op_sel_hi:[1,0]
	v_pk_mul_f32 v[16:17], v[16:17], v[122:123] op_sel_hi:[1,0]
	v_pk_mul_f32 v[38:39], v[144:145], v[122:123] op_sel_hi:[1,0]
	v_cvt_pk_bf16_f32 v60, v48, v49
	v_pk_mul_f32 v[30:31], v[30:31], v[122:123] op_sel_hi:[1,0]
	v_cvt_pk_bf16_f32 v61, v38, v39
	v_cvt_pk_bf16_f32 v62, v62, v63
	v_cvt_pk_bf16_f32 v63, v50, v51
	v_pk_mul_f32 v[28:29], v[28:29], v[122:123] op_sel_hi:[1,0]
	v_pk_mul_f32 v[18:19], v[18:19], v[122:123] op_sel_hi:[1,0]
	v_cvt_pk_bf16_f32 v48, v28, v29
	v_cvt_pk_bf16_f32 v49, v30, v31
	v_cvt_pk_bf16_f32 v50, v16, v17
	v_pk_mul_f32 v[16:17], v[20:21], v[122:123] op_sel_hi:[1,0]
	v_pk_mul_f32 v[38:39], v[120:121], v[122:123] op_sel_hi:[1,0]
	v_pk_mul_f32 v[20:21], v[36:37], v[122:123] op_sel_hi:[1,0]
	v_cvt_pk_bf16_f32 v51, v38, v39
; #define LAS __attribute__((address_space(3)))
; #define ATT_FENCE() asm volatile("" ::: "memory")
; DI void attn_worker(unsigned char* ws, LAS unsigned char* lds, LAS unsigned* qctr, int wave) {
;     ...
;         for (int sg = 0; sg < 8; ++sg) pa[sg] = __builtin_bit_cast(bf16x8, epi::pack8(s[2 * sg] * inv, s[2 * sg + 1] * inv));
;         f32x4 acc[8];
; #pragma unroll
;         for (int nt = 0; nt < 8; ++nt) acc[nt] = (f32x4){0.f, 0.f, 0.f, 0.f};
; #pragma unroll
;         for (int ch = 0; ch < 8; ++ch) {
;             if (ch + 2 < 8) { const int c2 = (ch + 2) % 3;
;                 ix[c2][0] = *(const LAS v4i*)(idl + 64 * kg + 8 * (ch + 2)); ix[c2][1] = *(const LAS v4i*)(idl + 64 * kg + 8 * (ch + 2) + 4);
; #pragma unroll
;                 for (int j = 0; j < 8; ++j) vv[c2][j] = *(const v4u*)(vbase + (size_t)ix[c2][j >> 2][j & 3] * KVD);
;                 ATT_FENCE(); }
; #pragma unroll
;             for (int j = 0; j < 8; ++j) *(LAS v4u*)(size_t)(vwb[j >> 2] + 64 * j) = vv[ch % 3][j];
;             v2u r0, r1, r2, r3, r4, r5, r6, r7, r8, r9, r10, r11, r12, r13, r14, r15;
;             asm volatile("ds_read_b64_tr_b16 %0, %16\n\tds_read_b64_tr_b16 %1, %18\n\tds_read_b64_tr_b16 %2, %17\n\tds_read_b64_tr_b16 %3, %19\n\t"
;                          "ds_read_b64_tr_b16 %4, %16 offset:512\n\tds_read_b64_tr_b16 %5, %18 offset:512\n\tds_read_b64_tr_b16 %6, %17 offset:512\n\tds_read_b64_tr_b16 %7, %19 offset:512\n\t"
;                          "ds_read_b64_tr_b16 %8, %16 offset:1024\n\tds_read_b64_tr_b16 %9, %18 offset:1024\n\tds_read_b64_tr_b16 %10, %17 offset:1024\n\tds_read_b64_tr_b16 %11, %19 offset:1024\n\t"
;                          "ds_read_b64_tr_b16 %12, %16 offset:1536\n\tds_read_b64_tr_b16 %13, %18 offset:1536\n\tds_read_b64_tr_b16 %14, %17 offset:1536\n\tds_read_b64_tr_b16 %15, %19 offset:1536\n\ts_waitcnt lgkmcnt(0)"
;                          : "=&v"(r0), "=&v"(r1), "=&v"(r2), "=&v"(r3), "=&v"(r4), "=&v"(r5), "=&v"(r6), "=&v"(r7), "=&v"(r8), "=&v"(r9), "=&v"(r10), "=&v"(r11), "=&v"(r12), "=&v"(r13), "=&v"(r14), "=&v"(r15)
;                          : "v"(vtb[0][0]), "v"(vtb[0][1]), "v"(vtb[1][0]), "v"(vtb[1][1]) : "memory");
;     ...
;             ATT_PV(0, r0, r1); ATT_PV(1, r2, r3); ATT_PV(2, r4, r5); ATT_PV(3, r6, r7); ATT_PV(4, r8, r9); ATT_PV(5, r10, r11); ATT_PV(6, r12, r13); ATT_PV(7, r14, r15);
	v_pk_mul_f32 v[22:23], v[22:23], v[122:123] op_sel_hi:[1,0]
	v_cvt_pk_bf16_f32 v36, v18, v19
	v_cvt_pk_bf16_f32 v37, v16, v17
	v_pk_mul_f32 v[16:17], v[34:35], v[122:123] op_sel_hi:[1,0]
	v_pk_mul_f32 v[18:19], v[32:33], v[122:123] op_sel_hi:[1,0]
	v_cvt_pk_bf16_f32 v38, v22, v23
	v_cvt_pk_bf16_f32 v39, v20, v21
	v_pk_mul_f32 v[20:21], v[156:157], v[122:123] op_sel_hi:[1,0]
	v_pk_mul_f32 v[22:23], v[152:153], v[122:123] op_sel_hi:[1,0]
	v_cvt_pk_bf16_f32 v32, v18, v19
	v_cvt_pk_bf16_f32 v33, v16, v17
	v_pk_mul_f32 v[16:17], v[158:159], v[122:123] op_sel_hi:[1,0]
	v_pk_mul_f32 v[18:19], v[154:155], v[122:123] op_sel_hi:[1,0]
	v_cvt_pk_bf16_f32 v34, v22, v23
	v_cvt_pk_bf16_f32 v35, v20, v21
	v_pk_mul_f32 v[20:21], v[164:165], v[122:123] op_sel_hi:[1,0]
	v_pk_mul_f32 v[22:23], v[160:161], v[122:123] op_sel_hi:[1,0]
	v_cvt_pk_bf16_f32 v28, v18, v19
	v_cvt_pk_bf16_f32 v29, v16, v17
	v_pk_mul_f32 v[16:17], v[166:167], v[122:123] op_sel_hi:[1,0]
	v_pk_mul_f32 v[18:19], v[162:163], v[122:123] op_sel_hi:[1,0]
	v_cvt_pk_bf16_f32 v30, v22, v23
	v_cvt_pk_bf16_f32 v31, v20, v21
	v_pk_mul_f32 v[120:121], v[170:171], v[122:123] op_sel_hi:[1,0]
	v_pk_mul_f32 v[22:23], v[168:169], v[122:123] op_sel_hi:[1,0]
	v_cvt_pk_bf16_f32 v20, v18, v19
	v_cvt_pk_bf16_f32 v21, v16, v17
	v_pk_mul_f32 v[18:19], v[74:75], v[122:123] op_sel_hi:[1,0]
	v_pk_mul_f32 v[16:17], v[72:73], v[122:123] op_sel_hi:[1,0]
	v_cvt_pk_bf16_f32 v22, v22, v23
	v_cvt_pk_bf16_f32 v23, v120, v121
	v_pk_mul_f32 v[70:71], v[70:71], v[122:123] op_sel_hi:[1,0]
	v_pk_mul_f32 v[68:69], v[68:69], v[122:123] op_sel_hi:[1,0]
	v_cvt_pk_bf16_f32 v16, v16, v17
	v_cvt_pk_bf16_f32 v17, v18, v19
	s_nop 0
	v_cvt_pk_bf16_f32 v18, v68, v69
	v_cvt_pk_bf16_f32 v19, v70, v71
	ds_read_b128 v[120:123], v182 offset:64
	ds_read_b128 v[124:127], v182 offset:80
	s_waitcnt lgkmcnt(1)
	v_lshl_add_u32 v68, v120, 10, v252
	v_lshl_add_u32 v70, v121, 10, v252
	v_lshl_add_u32 v120, v122, 10, v252
	v_lshl_add_u32 v128, v123, 10, v252
	s_waitcnt lgkmcnt(0)
	v_lshl_add_u32 v144, v124, 10, v252
	v_lshl_add_u32 v146, v125, 10, v252
	v_mov_b32_e32 v124, v146
	v_mov_b32_e32 v72, v70
	global_load_dwordx4 v[68:71], v68, s[100:101]
	s_nop 0
	global_load_dwordx4 v[72:75], v72, s[100:101]
	s_nop 0
	global_load_dwordx4 v[120:123], v120, s[100:101]
	s_nop 0
	global_load_dwordx4 v[128:131], v128, s[100:101]
	s_nop 0
	global_load_dwordx4 v[144:147], v144, s[100:101]
	s_nop 0
	global_load_dwordx4 v[148:151], v124, s[100:101]
	v_lshl_add_u32 v124, v126, 10, v252
	v_lshl_add_u32 v152, v127, 10, v252
	global_load_dwordx4 v[124:127], v124, s[100:101]
	s_nop 0
	global_load_dwordx4 v[152:155], v152, s[100:101]
	s_waitcnt vmcnt(23)
	ds_write_b128 v236, v[88:91]
	s_waitcnt vmcnt(22)
	ds_write_b128 v236, v[92:95] offset:64
	s_waitcnt vmcnt(21)
	ds_write_b128 v236, v[96:99] offset:128
	s_waitcnt vmcnt(20)
	ds_write_b128 v236, v[100:103] offset:192
	s_waitcnt vmcnt(19)
	ds_write_b128 v237, v[104:107] offset:256
	s_waitcnt vmcnt(18)
	ds_write_b128 v237, v[108:111] offset:320
	s_waitcnt vmcnt(17)
	ds_write_b128 v237, v[112:115] offset:384
	s_waitcnt vmcnt(16)
	ds_write_b128 v237, v[116:119] offset:448
	ds_read_b64_tr_b16 v[116:117], v176
	ds_read_b64_tr_b16 v[118:119], v178
	ds_read_b64_tr_b16 v[112:113], v177
	ds_read_b64_tr_b16 v[114:115], v179
	ds_read_b64_tr_b16 v[108:109], v176 offset:512
	ds_read_b64_tr_b16 v[110:111], v178 offset:512
	ds_read_b64_tr_b16 v[104:105], v177 offset:512
	ds_read_b64_tr_b16 v[106:107], v179 offset:512
	ds_read_b64_tr_b16 v[100:101], v176 offset:1024
	ds_read_b64_tr_b16 v[102:103], v178 offset:1024
	ds_read_b64_tr_b16 v[96:97], v177 offset:1024
	ds_read_b64_tr_b16 v[98:99], v179 offset:1024
	ds_read_b64_tr_b16 v[92:93], v176 offset:1536
	ds_read_b64_tr_b16 v[94:95], v178 offset:1536
	ds_read_b64_tr_b16 v[88:89], v177 offset:1536
	ds_read_b64_tr_b16 v[90:91], v179 offset:1536
	s_waitcnt lgkmcnt(0)
	ds_read_b128 v[156:159], v182 offset:96
	ds_read_b128 v[164:167], v182 offset:112
	v_mfma_f32_16x16x32_bf16 v[116:119], v[64:67], v[116:119], 0
	s_waitcnt lgkmcnt(1)
	v_mfma_f32_16x16x32_bf16 v[112:115], v[64:67], v[112:115], 0
	v_lshl_add_u32 v168, v159, 10, v252
	s_waitcnt lgkmcnt(0)
	v_lshl_add_u32 v240, v164, 10, v252
	v_mfma_f32_16x16x32_bf16 v[108:111], v[64:67], v[108:111], 0
	v_lshl_add_u32 v242, v165, 10, v252
	v_mfma_f32_16x16x32_bf16 v[104:107], v[64:67], v[104:107], 0
	v_mov_b32_e32 v164, v242
	v_mfma_f32_16x16x32_bf16 v[100:103], v[64:67], v[100:103], 0
	v_lshl_add_u32 v248, v167, 10, v252
	v_mfma_f32_16x16x32_bf16 v[96:99], v[64:67], v[96:99], 0
	v_mfma_f32_16x16x32_bf16 v[92:95], v[64:67], v[92:95], 0
	v_mfma_f32_16x16x32_bf16 v[160:163], v[64:67], v[88:91], 0
	v_lshl_add_u32 v64, v156, 10, v252
	v_lshl_add_u32 v66, v157, 10, v252
	v_lshl_add_u32 v156, v158, 10, v252
	v_mov_b32_e32 v88, v66
	global_load_dwordx4 v[64:67], v64, s[100:101]
	s_nop 0
	global_load_dwordx4 v[88:91], v88, s[100:101]
	s_nop 0
	global_load_dwordx4 v[156:159], v156, s[100:101]
	s_nop 0
	global_load_dwordx4 v[168:171], v168, s[100:101]
	s_nop 0
	global_load_dwordx4 v[240:243], v240, s[100:101]
	s_nop 0
	global_load_dwordx4 v[244:247], v164, s[100:101]
	v_lshl_add_u32 v164, v166, 10, v252
	global_load_dwordx4 v[164:167], v164, s[100:101]
	s_nop 0
	global_load_dwordx4 v[248:251], v248, s[100:101]
	s_waitcnt vmcnt(23)
	ds_write_b128 v236, v[24:27]
	s_waitcnt vmcnt(22)
	ds_write_b128 v236, v[40:43] offset:64
	s_waitcnt vmcnt(21)
	ds_write_b128 v236, v[44:47] offset:128
	s_waitcnt vmcnt(20)
	ds_write_b128 v236, v[76:79] offset:192
	s_waitcnt vmcnt(19)
	ds_write_b128 v237, v[80:83] offset:256
	s_waitcnt vmcnt(18)
	ds_write_b128 v237, v[84:87] offset:320
	s_waitcnt vmcnt(17)
; #define LAS __attribute__((address_space(3)))
; #define ATT_FENCE() asm volatile("" ::: "memory")
; #define ATT_PV(nt_, ra_, rb_) acc[nt_] = __builtin_amdgcn_mfma_f32_16x16x32_bf16(pa[ch], __builtin_bit_cast(bf16x8, (v4u){ra_.x, ra_.y, rb_.x, rb_.y}), acc[nt_], 0, 0, 0)
; DI void attn_worker(unsigned char* ws, LAS unsigned char* lds, LAS unsigned* qctr, int wave) {
;     ...
;         for (int ch = 0; ch < 8; ++ch) {
;             if (ch + 2 < 8) { const int c2 = (ch + 2) % 3;
;                 ix[c2][0] = *(const LAS v4i*)(idl + 64 * kg + 8 * (ch + 2)); ix[c2][1] = *(const LAS v4i*)(idl + 64 * kg + 8 * (ch + 2) + 4);
; #pragma unroll
;                 for (int j = 0; j < 8; ++j) vv[c2][j] = *(const v4u*)(vbase + (size_t)ix[c2][j >> 2][j & 3] * KVD);
;                 ATT_FENCE(); }
; #pragma unroll
;             for (int j = 0; j < 8; ++j) *(LAS v4u*)(size_t)(vwb[j >> 2] + 64 * j) = vv[ch % 3][j];
;             v2u r0, r1, r2, r3, r4, r5, r6, r7, r8, r9, r10, r11, r12, r13, r14, r15;
;             asm volatile("ds_read_b64_tr_b16 %0, %16\n\tds_read_b64_tr_b16 %1, %18\n\tds_read_b64_tr_b16 %2, %17\n\tds_read_b64_tr_b16 %3, %19\n\t"
;                          "ds_read_b64_tr_b16 %4, %16 offset:512\n\tds_read_b64_tr_b16 %5, %18 offset:512\n\tds_read_b64_tr_b16 %6, %17 offset:512\n\tds_read_b64_tr_b16 %7, %19 offset:512\n\t"
;                          "ds_read_b64_tr_b16 %8, %16 offset:1024\n\tds_read_b64_tr_b16 %9, %18 offset:1024\n\tds_read_b64_tr_b16 %10, %17 offset:1024\n\tds_read_b64_tr_b16 %11, %19 offset:1024\n\t"
;                          "ds_read_b64_tr_b16 %12, %16 offset:1536\n\tds_read_b64_tr_b16 %13, %18 offset:1536\n\tds_read_b64_tr_b16 %14, %17 offset:1536\n\tds_read_b64_tr_b16 %15, %19 offset:1536\n\ts_waitcnt lgkmcnt(0)"
;                          : "=&v"(r0), "=&v"(r1), "=&v"(r2), "=&v"(r3), "=&v"(r4), "=&v"(r5), "=&v"(r6), "=&v"(r7), "=&v"(r8), "=&v"(r9), "=&v"(r10), "=&v"(r11), "=&v"(r12), "=&v"(r13), "=&v"(r14), "=&v"(r15)
;                          : "v"(vtb[0][0]), "v"(vtb[0][1]), "v"(vtb[1][0]), "v"(vtb[1][1]) : "memory");
;     ...
;             ATT_PV(0, r0, r1); ATT_PV(1, r2, r3); ATT_PV(2, r4, r5); ATT_PV(3, r6, r7); ATT_PV(4, r8, r9); ATT_PV(5, r10, r11); ATT_PV(6, r12, r13); ATT_PV(7, r14, r15);
	ds_write_b128 v237, v[52:55] offset:384
	s_waitcnt vmcnt(16)
	ds_write_b128 v237, v[56:59] offset:448
	ds_read_b64_tr_b16 v[84:85], v176
	ds_read_b64_tr_b16 v[86:87], v178
	ds_read_b64_tr_b16 v[80:81], v177
	ds_read_b64_tr_b16 v[82:83], v179
	ds_read_b64_tr_b16 v[76:77], v176 offset:512
	ds_read_b64_tr_b16 v[78:79], v178 offset:512
	ds_read_b64_tr_b16 v[56:57], v177 offset:512
	ds_read_b64_tr_b16 v[58:59], v179 offset:512
	ds_read_b64_tr_b16 v[52:53], v176 offset:1024
	ds_read_b64_tr_b16 v[54:55], v178 offset:1024
	ds_read_b64_tr_b16 v[44:45], v177 offset:1024
	ds_read_b64_tr_b16 v[46:47], v179 offset:1024
	ds_read_b64_tr_b16 v[40:41], v176 offset:1536
	ds_read_b64_tr_b16 v[42:43], v178 offset:1536
	ds_read_b64_tr_b16 v[24:25], v177 offset:1536
	ds_read_b64_tr_b16 v[26:27], v179 offset:1536
	s_waitcnt lgkmcnt(0)
	s_nop 0
	v_mfma_f32_16x16x32_bf16 v[52:55], v[60:63], v[52:55], v[100:103]
	v_mfma_f32_16x16x32_bf16 v[44:47], v[60:63], v[44:47], v[96:99]
	s_nop 1
	ds_read_b128 v[100:103], v182 offset:144
	ds_read_b128 v[96:99], v182 offset:128
	v_mfma_f32_16x16x32_bf16 v[84:87], v[60:63], v[84:87], v[116:119]
	v_mfma_f32_16x16x32_bf16 v[80:83], v[60:63], v[80:83], v[112:115]
	s_waitcnt lgkmcnt(1)
	s_nop 0
	v_lshl_add_u32 v116, v103, 10, v252
	v_mfma_f32_16x16x32_bf16 v[76:79], v[60:63], v[76:79], v[108:111]
	v_mfma_f32_16x16x32_bf16 v[56:59], v[60:63], v[56:59], v[104:107]
	s_nop 1
	v_lshl_add_u32 v108, v100, 10, v252
	v_mfma_f32_16x16x32_bf16 v[92:95], v[60:63], v[40:43], v[92:95]
	s_waitcnt lgkmcnt(0)
	v_lshl_add_u32 v104, v99, 10, v252
	v_lshl_add_u32 v110, v101, 10, v252
	v_mfma_f32_16x16x32_bf16 v[60:63], v[60:63], v[24:27], v[160:163]
	v_lshl_add_u32 v24, v96, 10, v252
	v_lshl_add_u32 v26, v97, 10, v252
	v_lshl_add_u32 v96, v98, 10, v252
	v_mov_b32_e32 v100, v110
	v_mov_b32_e32 v40, v26
	global_load_dwordx4 v[24:27], v24, s[100:101]
	s_nop 0
	global_load_dwordx4 v[40:43], v40, s[100:101]
	s_nop 0
	global_load_dwordx4 v[96:99], v96, s[100:101]
	s_nop 0
	global_load_dwordx4 v[104:107], v104, s[100:101]
	s_nop 0
	global_load_dwordx4 v[108:111], v108, s[100:101]
	s_nop 0
	global_load_dwordx4 v[112:115], v100, s[100:101]
	v_lshl_add_u32 v100, v102, 10, v252
	global_load_dwordx4 v[100:103], v100, s[100:101]
	s_nop 0
	global_load_dwordx4 v[116:119], v116, s[100:101]
	s_waitcnt vmcnt(23)
	ds_write_b128 v236, v[68:71]
	s_waitcnt vmcnt(22)
	ds_write_b128 v236, v[72:75] offset:64
	s_waitcnt vmcnt(21)
	ds_write_b128 v236, v[120:123] offset:128
	s_waitcnt vmcnt(20)
	ds_write_b128 v236, v[128:131] offset:192
	s_waitcnt vmcnt(19)
	ds_write_b128 v237, v[144:147] offset:256
	s_waitcnt vmcnt(18)
	ds_write_b128 v237, v[148:151] offset:320
	s_waitcnt vmcnt(17)
	ds_write_b128 v237, v[124:127] offset:384
	s_waitcnt vmcnt(16)
	ds_write_b128 v237, v[152:155] offset:448
	ds_read_b64_tr_b16 v[152:153], v176
	ds_read_b64_tr_b16 v[154:155], v178
	ds_read_b64_tr_b16 v[148:149], v177
	ds_read_b64_tr_b16 v[150:151], v179
	ds_read_b64_tr_b16 v[144:145], v176 offset:512
	ds_read_b64_tr_b16 v[146:147], v178 offset:512
	ds_read_b64_tr_b16 v[128:129], v177 offset:512
	ds_read_b64_tr_b16 v[130:131], v179 offset:512
	ds_read_b64_tr_b16 v[124:125], v176 offset:1024
	ds_read_b64_tr_b16 v[126:127], v178 offset:1024
	ds_read_b64_tr_b16 v[120:121], v177 offset:1024
	ds_read_b64_tr_b16 v[122:123], v179 offset:1024
	ds_read_b64_tr_b16 v[72:73], v176 offset:1536
	ds_read_b64_tr_b16 v[74:75], v178 offset:1536
	ds_read_b64_tr_b16 v[68:69], v177 offset:1536
	ds_read_b64_tr_b16 v[70:71], v179 offset:1536
	s_waitcnt lgkmcnt(0)
	s_nop 0
	v_mfma_f32_16x16x32_bf16 v[72:75], v[48:51], v[72:75], v[92:95]
	s_nop 2
	ds_read_b128 v[92:95], v182 offset:160
	v_mfma_f32_16x16x32_bf16 v[60:63], v[48:51], v[68:71], v[60:63]
	ds_read_b128 v[68:71], v182 offset:176
	v_mfma_f32_16x16x32_bf16 v[56:59], v[48:51], v[128:131], v[56:59]
	s_waitcnt lgkmcnt(0)
	v_lshl_add_u32 v128, v68, 10, v252
	v_mfma_f32_16x16x32_bf16 v[52:55], v[48:51], v[124:127], v[52:55]
	v_lshl_add_u32 v124, v95, 10, v252
	v_mfma_f32_16x16x32_bf16 v[120:123], v[48:51], v[120:123], v[44:47]
	v_lshl_add_u32 v130, v69, 10, v252
	v_mov_b32_e32 v68, v130
	v_lshl_add_u32 v44, v92, 10, v252
	v_lshl_add_u32 v46, v93, 10, v252
	v_lshl_add_u32 v92, v94, 10, v252
	v_mfma_f32_16x16x32_bf16 v[84:87], v[48:51], v[152:155], v[84:87]
	v_mfma_f32_16x16x32_bf16 v[80:83], v[48:51], v[148:151], v[80:83]
	v_mfma_f32_16x16x32_bf16 v[76:79], v[48:51], v[144:147], v[76:79]
	v_mov_b32_e32 v48, v46
	global_load_dwordx4 v[44:47], v44, s[100:101]
	s_nop 0
	global_load_dwordx4 v[48:51], v48, s[100:101]
	s_nop 0
	global_load_dwordx4 v[92:95], v92, s[100:101]
	s_nop 0
	global_load_dwordx4 v[124:127], v124, s[100:101]
	s_nop 0
	global_load_dwordx4 v[128:131], v128, s[100:101]
	s_nop 0
	global_load_dwordx4 v[144:147], v68, s[100:101]
	v_lshl_add_u32 v68, v70, 10, v252
	v_lshl_add_u32 v148, v71, 10, v252
	global_load_dwordx4 v[68:71], v68, s[100:101]
	s_nop 0
	global_load_dwordx4 v[148:151], v148, s[100:101]
	s_waitcnt vmcnt(23)
	ds_write_b128 v236, v[64:67]
	s_waitcnt vmcnt(22)
	ds_write_b128 v236, v[88:91] offset:64
	s_waitcnt vmcnt(21)
	ds_write_b128 v236, v[156:159] offset:128
	s_waitcnt vmcnt(20)
	ds_write_b128 v236, v[168:171] offset:192
	s_waitcnt vmcnt(19)
	ds_write_b128 v237, v[240:243] offset:256
	s_waitcnt vmcnt(18)
	ds_write_b128 v237, v[244:247] offset:320
	s_waitcnt vmcnt(17)
	ds_write_b128 v237, v[164:167] offset:384
	s_waitcnt vmcnt(16)
; #define LAS __attribute__((address_space(3)))
; #define ATT_FENCE() asm volatile("" ::: "memory")
; #define ATT_PV(nt_, ra_, rb_) acc[nt_] = __builtin_amdgcn_mfma_f32_16x16x32_bf16(pa[ch], __builtin_bit_cast(bf16x8, (v4u){ra_.x, ra_.y, rb_.x, rb_.y}), acc[nt_], 0, 0, 0)
; DI void attn_worker(unsigned char* ws, LAS unsigned char* lds, LAS unsigned* qctr, int wave) {
;     ...
;         for (int ch = 0; ch < 8; ++ch) {
;             if (ch + 2 < 8) { const int c2 = (ch + 2) % 3;
;                 ix[c2][0] = *(const LAS v4i*)(idl + 64 * kg + 8 * (ch + 2)); ix[c2][1] = *(const LAS v4i*)(idl + 64 * kg + 8 * (ch + 2) + 4);
; #pragma unroll
;                 for (int j = 0; j < 8; ++j) vv[c2][j] = *(const v4u*)(vbase + (size_t)ix[c2][j >> 2][j & 3] * KVD);
;                 ATT_FENCE(); }
; #pragma unroll
;             for (int j = 0; j < 8; ++j) *(LAS v4u*)(size_t)(vwb[j >> 2] + 64 * j) = vv[ch % 3][j];
;             v2u r0, r1, r2, r3, r4, r5, r6, r7, r8, r9, r10, r11, r12, r13, r14, r15;
;             asm volatile("ds_read_b64_tr_b16 %0, %16\n\tds_read_b64_tr_b16 %1, %18\n\tds_read_b64_tr_b16 %2, %17\n\tds_read_b64_tr_b16 %3, %19\n\t"
;                          "ds_read_b64_tr_b16 %4, %16 offset:512\n\tds_read_b64_tr_b16 %5, %18 offset:512\n\tds_read_b64_tr_b16 %6, %17 offset:512\n\tds_read_b64_tr_b16 %7, %19 offset:512\n\t"
;                          "ds_read_b64_tr_b16 %8, %16 offset:1024\n\tds_read_b64_tr_b16 %9, %18 offset:1024\n\tds_read_b64_tr_b16 %10, %17 offset:1024\n\tds_read_b64_tr_b16 %11, %19 offset:1024\n\t"
;                          "ds_read_b64_tr_b16 %12, %16 offset:1536\n\tds_read_b64_tr_b16 %13, %18 offset:1536\n\tds_read_b64_tr_b16 %14, %17 offset:1536\n\tds_read_b64_tr_b16 %15, %19 offset:1536\n\ts_waitcnt lgkmcnt(0)"
;                          : "=&v"(r0), "=&v"(r1), "=&v"(r2), "=&v"(r3), "=&v"(r4), "=&v"(r5), "=&v"(r6), "=&v"(r7), "=&v"(r8), "=&v"(r9), "=&v"(r10), "=&v"(r11), "=&v"(r12), "=&v"(r13), "=&v"(r14), "=&v"(r15)
;                          : "v"(vtb[0][0]), "v"(vtb[0][1]), "v"(vtb[1][0]), "v"(vtb[1][1]) : "memory");
;     ...
;             ATT_PV(0, r0, r1); ATT_PV(1, r2, r3); ATT_PV(2, r4, r5); ATT_PV(3, r6, r7); ATT_PV(4, r8, r9); ATT_PV(5, r10, r11); ATT_PV(6, r12, r13); ATT_PV(7, r14, r15);
	ds_write_b128 v237, v[248:251] offset:448
	ds_read_b64_tr_b16 v[240:241], v176
	ds_read_b64_tr_b16 v[242:243], v178
	ds_read_b64_tr_b16 v[168:169], v177
	ds_read_b64_tr_b16 v[170:171], v179
	ds_read_b64_tr_b16 v[164:165], v176 offset:512
	ds_read_b64_tr_b16 v[166:167], v178 offset:512
	ds_read_b64_tr_b16 v[160:161], v177 offset:512
	ds_read_b64_tr_b16 v[162:163], v179 offset:512
	ds_read_b64_tr_b16 v[156:157], v176 offset:1024
	ds_read_b64_tr_b16 v[158:159], v178 offset:1024
	ds_read_b64_tr_b16 v[152:153], v177 offset:1024
	ds_read_b64_tr_b16 v[154:155], v179 offset:1024
	ds_read_b64_tr_b16 v[88:89], v176 offset:1536
	ds_read_b64_tr_b16 v[90:91], v178 offset:1536
	ds_read_b64_tr_b16 v[64:65], v177 offset:1536
	ds_read_b64_tr_b16 v[66:67], v179 offset:1536
	s_waitcnt lgkmcnt(0)
	s_nop 0
	v_mfma_f32_16x16x32_bf16 v[72:75], v[36:39], v[88:91], v[72:75]
	ds_read_b128 v[88:91], v182 offset:192
	v_mfma_f32_16x16x32_bf16 v[84:87], v[36:39], v[240:243], v[84:87]
	v_mfma_f32_16x16x32_bf16 v[80:83], v[36:39], v[168:171], v[80:83]
	v_mfma_f32_16x16x32_bf16 v[76:79], v[36:39], v[164:167], v[76:79]
	v_mfma_f32_16x16x32_bf16 v[56:59], v[36:39], v[160:163], v[56:59]
	v_mfma_f32_16x16x32_bf16 v[52:55], v[36:39], v[156:159], v[52:55]
	v_mfma_f32_16x16x32_bf16 v[120:123], v[36:39], v[152:155], v[120:123]
	v_mfma_f32_16x16x32_bf16 v[36:39], v[36:39], v[64:67], v[60:63]
	s_nop 2
	ds_read_b128 v[60:63], v182 offset:208
	s_waitcnt lgkmcnt(1)
	v_lshl_add_u32 v64, v88, 10, v252
	v_lshl_add_u32 v66, v89, 10, v252
	v_mov_b32_e32 v88, v66
	global_load_dwordx4 v[64:67], v64, s[100:101]
	s_nop 0
	global_load_dwordx4 v[152:155], v88, s[100:101]
	v_lshl_add_u32 v88, v90, 10, v252
	v_lshl_add_u32 v156, v91, 10, v252
	s_waitcnt lgkmcnt(0)
	v_lshl_add_u32 v160, v60, 10, v252
	v_lshl_add_u32 v162, v61, 10, v252
	v_mov_b32_e32 v60, v162
	global_load_dwordx4 v[88:91], v88, s[100:101]
	s_nop 0
	global_load_dwordx4 v[156:159], v156, s[100:101]
	s_nop 0
	global_load_dwordx4 v[160:163], v160, s[100:101]
	s_nop 0
	global_load_dwordx4 v[164:167], v60, s[100:101]
	v_lshl_add_u32 v60, v62, 10, v252
	v_lshl_add_u32 v168, v63, 10, v252
	global_load_dwordx4 v[60:63], v60, s[100:101]
	s_nop 0
	global_load_dwordx4 v[168:171], v168, s[100:101]
	s_waitcnt vmcnt(23)
	ds_write_b128 v236, v[24:27]
	s_waitcnt vmcnt(22)
	ds_write_b128 v236, v[40:43] offset:64
	s_waitcnt vmcnt(21)
	ds_write_b128 v236, v[96:99] offset:128
	s_waitcnt vmcnt(20)
	ds_write_b128 v236, v[104:107] offset:192
	s_waitcnt vmcnt(19)
	ds_write_b128 v237, v[108:111] offset:256
	s_waitcnt vmcnt(18)
	ds_write_b128 v237, v[112:115] offset:320
	s_waitcnt vmcnt(17)
	ds_write_b128 v237, v[100:103] offset:384
	s_waitcnt vmcnt(16)
	ds_write_b128 v237, v[116:119] offset:448
	ds_read_b64_tr_b16 v[116:117], v176
	ds_read_b64_tr_b16 v[118:119], v178
	ds_read_b64_tr_b16 v[112:113], v177
	ds_read_b64_tr_b16 v[114:115], v179
	ds_read_b64_tr_b16 v[108:109], v176 offset:512
	ds_read_b64_tr_b16 v[110:111], v178 offset:512
	ds_read_b64_tr_b16 v[104:105], v177 offset:512
	ds_read_b64_tr_b16 v[106:107], v179 offset:512
	ds_read_b64_tr_b16 v[100:101], v176 offset:1024
	ds_read_b64_tr_b16 v[102:103], v178 offset:1024
	ds_read_b64_tr_b16 v[96:97], v177 offset:1024
	ds_read_b64_tr_b16 v[98:99], v179 offset:1024
	ds_read_b64_tr_b16 v[40:41], v176 offset:1536
	ds_read_b64_tr_b16 v[42:43], v178 offset:1536
	ds_read_b64_tr_b16 v[24:25], v177 offset:1536
	ds_read_b64_tr_b16 v[26:27], v179 offset:1536
	s_waitcnt lgkmcnt(0)
	s_nop 0
	v_mfma_f32_16x16x32_bf16 v[40:43], v[32:35], v[40:43], v[72:75]
	s_nop 2
	ds_read_b128 v[72:75], v182 offset:224
	v_mfma_f32_16x16x32_bf16 v[84:87], v[32:35], v[116:119], v[84:87]
	v_mfma_f32_16x16x32_bf16 v[80:83], v[32:35], v[112:115], v[80:83]
	v_mfma_f32_16x16x32_bf16 v[76:79], v[32:35], v[108:111], v[76:79]
	v_mfma_f32_16x16x32_bf16 v[56:59], v[32:35], v[104:107], v[56:59]
	v_mfma_f32_16x16x32_bf16 v[52:55], v[32:35], v[100:103], v[52:55]
	v_mfma_f32_16x16x32_bf16 v[96:99], v[32:35], v[96:99], v[120:123]
	v_mfma_f32_16x16x32_bf16 v[24:27], v[32:35], v[24:27], v[36:39]
	ds_read_b128 v[32:35], v182 offset:240
	s_waitcnt lgkmcnt(1)
	v_lshl_add_u32 v104, v75, 10, v252
	v_lshl_add_u32 v36, v72, 10, v252
	v_lshl_add_u32 v38, v73, 10, v252
	v_mov_b32_e32 v72, v38
	global_load_dwordx4 v[36:39], v36, s[100:101]
	s_nop 0
	global_load_dwordx4 v[100:103], v72, s[100:101]
	v_lshl_add_u32 v72, v74, 10, v252
	s_waitcnt lgkmcnt(0)
	v_lshl_add_u32 v108, v32, 10, v252
	v_lshl_add_u32 v110, v33, 10, v252
	v_mov_b32_e32 v32, v110
	global_load_dwordx4 v[72:75], v72, s[100:101]
	s_nop 0
	global_load_dwordx4 v[104:107], v104, s[100:101]
	s_nop 0
	global_load_dwordx4 v[108:111], v108, s[100:101]
	s_nop 0
	global_load_dwordx4 v[112:115], v32, s[100:101]
	v_lshl_add_u32 v32, v34, 10, v252
	v_lshl_add_u32 v116, v35, 10, v252
	global_load_dwordx4 v[32:35], v32, s[100:101]
	s_nop 0
	global_load_dwordx4 v[116:119], v116, s[100:101]
	s_waitcnt vmcnt(23)
	ds_write_b128 v236, v[44:47]
	s_waitcnt vmcnt(22)
	ds_write_b128 v236, v[48:51] offset:64
	s_waitcnt vmcnt(21)
	ds_write_b128 v236, v[92:95] offset:128
	s_waitcnt vmcnt(20)
	ds_write_b128 v236, v[124:127] offset:192
	s_waitcnt vmcnt(19)
	ds_write_b128 v237, v[128:131] offset:256
	s_waitcnt vmcnt(18)
	ds_write_b128 v237, v[144:147] offset:320
	s_waitcnt vmcnt(17)
	ds_write_b128 v237, v[68:71] offset:384
	s_waitcnt vmcnt(16)
; #define LAS __attribute__((address_space(3)))
; #define ATT_FENCE() asm volatile("" ::: "memory")
; #define ATT_PV(nt_, ra_, rb_) acc[nt_] = __builtin_amdgcn_mfma_f32_16x16x32_bf16(pa[ch], __builtin_bit_cast(bf16x8, (v4u){ra_.x, ra_.y, rb_.x, rb_.y}), acc[nt_], 0, 0, 0)
; DI void attn_worker(unsigned char* ws, LAS unsigned char* lds, LAS unsigned* qctr, int wave) {
;     ...
;         for (int ch = 0; ch < 8; ++ch) {
;             if (ch + 2 < 8) { const int c2 = (ch + 2) % 3;
;                 ix[c2][0] = *(const LAS v4i*)(idl + 64 * kg + 8 * (ch + 2)); ix[c2][1] = *(const LAS v4i*)(idl + 64 * kg + 8 * (ch + 2) + 4);
; #pragma unroll
;                 for (int j = 0; j < 8; ++j) vv[c2][j] = *(const v4u*)(vbase + (size_t)ix[c2][j >> 2][j & 3] * KVD);
;                 ATT_FENCE(); }
; #pragma unroll
;             for (int j = 0; j < 8; ++j) *(LAS v4u*)(size_t)(vwb[j >> 2] + 64 * j) = vv[ch % 3][j];
;             v2u r0, r1, r2, r3, r4, r5, r6, r7, r8, r9, r10, r11, r12, r13, r14, r15;
;             asm volatile("ds_read_b64_tr_b16 %0, %16\n\tds_read_b64_tr_b16 %1, %18\n\tds_read_b64_tr_b16 %2, %17\n\tds_read_b64_tr_b16 %3, %19\n\t"
;                          "ds_read_b64_tr_b16 %4, %16 offset:512\n\tds_read_b64_tr_b16 %5, %18 offset:512\n\tds_read_b64_tr_b16 %6, %17 offset:512\n\tds_read_b64_tr_b16 %7, %19 offset:512\n\t"
;                          "ds_read_b64_tr_b16 %8, %16 offset:1024\n\tds_read_b64_tr_b16 %9, %18 offset:1024\n\tds_read_b64_tr_b16 %10, %17 offset:1024\n\tds_read_b64_tr_b16 %11, %19 offset:1024\n\t"
;                          "ds_read_b64_tr_b16 %12, %16 offset:1536\n\tds_read_b64_tr_b16 %13, %18 offset:1536\n\tds_read_b64_tr_b16 %14, %17 offset:1536\n\tds_read_b64_tr_b16 %15, %19 offset:1536\n\ts_waitcnt lgkmcnt(0)"
;                          : "=&v"(r0), "=&v"(r1), "=&v"(r2), "=&v"(r3), "=&v"(r4), "=&v"(r5), "=&v"(r6), "=&v"(r7), "=&v"(r8), "=&v"(r9), "=&v"(r10), "=&v"(r11), "=&v"(r12), "=&v"(r13), "=&v"(r14), "=&v"(r15)
;                          : "v"(vtb[0][0]), "v"(vtb[0][1]), "v"(vtb[1][0]), "v"(vtb[1][1]) : "memory");
;     ...
;             ATT_PV(0, r0, r1); ATT_PV(1, r2, r3); ATT_PV(2, r4, r5); ATT_PV(3, r6, r7); ATT_PV(4, r8, r9); ATT_PV(5, r10, r11); ATT_PV(6, r12, r13); ATT_PV(7, r14, r15);
;     ...
;         }
;         { LAS unsigned short* ob = (LAS unsigned short*)(lds + 2048);
;           if (lane < 16) {
	ds_write_b128 v237, v[148:151] offset:448
	ds_read_b64_tr_b16 v[144:145], v176
	ds_read_b64_tr_b16 v[146:147], v178
	ds_read_b64_tr_b16 v[128:129], v177
	ds_read_b64_tr_b16 v[130:131], v179
	ds_read_b64_tr_b16 v[124:125], v176 offset:512
	ds_read_b64_tr_b16 v[126:127], v178 offset:512
	ds_read_b64_tr_b16 v[120:121], v177 offset:512
	ds_read_b64_tr_b16 v[122:123], v179 offset:512
	ds_read_b64_tr_b16 v[92:93], v176 offset:1024
	ds_read_b64_tr_b16 v[94:95], v178 offset:1024
	ds_read_b64_tr_b16 v[68:69], v177 offset:1024
	ds_read_b64_tr_b16 v[70:71], v179 offset:1024
	ds_read_b64_tr_b16 v[48:49], v176 offset:1536
	ds_read_b64_tr_b16 v[50:51], v178 offset:1536
	ds_read_b64_tr_b16 v[44:45], v177 offset:1536
	ds_read_b64_tr_b16 v[46:47], v179 offset:1536
	s_waitcnt lgkmcnt(0)
	s_waitcnt vmcnt(15)
	ds_write_b128 v236, v[64:67]
	s_waitcnt vmcnt(14)
	ds_write_b128 v236, v[152:155] offset:64
	s_waitcnt vmcnt(13)
	ds_write_b128 v236, v[88:91] offset:128
	s_waitcnt vmcnt(12)
	ds_write_b128 v236, v[156:159] offset:192
	s_waitcnt vmcnt(11)
	ds_write_b128 v237, v[160:163] offset:256
	s_waitcnt vmcnt(10)
	ds_write_b128 v237, v[164:167] offset:320
	s_waitcnt vmcnt(9)
	ds_write_b128 v237, v[60:63] offset:384
	s_waitcnt vmcnt(8)
	ds_write_b128 v237, v[168:171] offset:448
	v_mfma_f32_16x16x32_bf16 v[84:87], v[28:31], v[144:147], v[84:87]
	v_mfma_f32_16x16x32_bf16 v[80:83], v[28:31], v[128:131], v[80:83]
	v_mfma_f32_16x16x32_bf16 v[76:79], v[28:31], v[124:127], v[76:79]
	v_mfma_f32_16x16x32_bf16 v[56:59], v[28:31], v[120:123], v[56:59]
	v_mfma_f32_16x16x32_bf16 v[52:55], v[28:31], v[92:95], v[52:55]
	v_mfma_f32_16x16x32_bf16 v[68:71], v[28:31], v[68:71], v[96:99]
	v_mfma_f32_16x16x32_bf16 v[40:43], v[28:31], v[48:51], v[40:43]
	v_mfma_f32_16x16x32_bf16 v[24:27], v[28:31], v[44:47], v[24:27]
	ds_read_b64_tr_b16 v[96:97], v176
	ds_read_b64_tr_b16 v[98:99], v178
	ds_read_b64_tr_b16 v[92:93], v177
	ds_read_b64_tr_b16 v[94:95], v179
	ds_read_b64_tr_b16 v[88:89], v176 offset:512
	ds_read_b64_tr_b16 v[90:91], v178 offset:512
	ds_read_b64_tr_b16 v[64:65], v177 offset:512
	ds_read_b64_tr_b16 v[66:67], v179 offset:512
	ds_read_b64_tr_b16 v[60:61], v176 offset:1024
	ds_read_b64_tr_b16 v[62:63], v178 offset:1024
	ds_read_b64_tr_b16 v[48:49], v177 offset:1024
	ds_read_b64_tr_b16 v[50:51], v179 offset:1024
	ds_read_b64_tr_b16 v[44:45], v176 offset:1536
	ds_read_b64_tr_b16 v[46:47], v178 offset:1536
	ds_read_b64_tr_b16 v[28:29], v177 offset:1536
	ds_read_b64_tr_b16 v[30:31], v179 offset:1536
	s_waitcnt lgkmcnt(0)
	s_waitcnt vmcnt(7)
	ds_write_b128 v236, v[36:39]
	s_waitcnt vmcnt(6)
	ds_write_b128 v236, v[100:103] offset:64
	s_waitcnt vmcnt(5)
	ds_write_b128 v236, v[72:75] offset:128
	s_waitcnt vmcnt(4)
	ds_write_b128 v236, v[104:107] offset:192
	s_waitcnt vmcnt(3)
	ds_write_b128 v237, v[108:111] offset:256
	s_waitcnt vmcnt(2)
	ds_write_b128 v237, v[112:115] offset:320
	s_waitcnt vmcnt(1)
	ds_write_b128 v237, v[32:35] offset:384
	s_waitcnt vmcnt(0)
	ds_write_b128 v237, v[116:119] offset:448
	v_mfma_f32_16x16x32_bf16 v[84:87], v[20:23], v[96:99], v[84:87]
	v_mfma_f32_16x16x32_bf16 v[80:83], v[20:23], v[92:95], v[80:83]
	v_mfma_f32_16x16x32_bf16 v[76:79], v[20:23], v[88:91], v[76:79]
	v_mfma_f32_16x16x32_bf16 v[56:59], v[20:23], v[64:67], v[56:59]
	v_mfma_f32_16x16x32_bf16 v[52:55], v[20:23], v[60:63], v[52:55]
	v_mfma_f32_16x16x32_bf16 v[48:51], v[20:23], v[48:51], v[68:71]
	v_mfma_f32_16x16x32_bf16 v[60:63], v[20:23], v[44:47], v[40:43]
	v_mfma_f32_16x16x32_bf16 v[64:67], v[20:23], v[28:31], v[24:27]
	ds_read_b64_tr_b16 v[44:45], v176
	ds_read_b64_tr_b16 v[46:47], v178
	ds_read_b64_tr_b16 v[40:41], v177
	ds_read_b64_tr_b16 v[42:43], v179
	ds_read_b64_tr_b16 v[36:37], v176 offset:512
	ds_read_b64_tr_b16 v[38:39], v178 offset:512
	ds_read_b64_tr_b16 v[32:33], v177 offset:512
	ds_read_b64_tr_b16 v[34:35], v179 offset:512
	ds_read_b64_tr_b16 v[28:29], v176 offset:1024
	ds_read_b64_tr_b16 v[30:31], v178 offset:1024
	ds_read_b64_tr_b16 v[24:25], v177 offset:1024
	ds_read_b64_tr_b16 v[26:27], v179 offset:1024
	ds_read_b64_tr_b16 v[20:21], v176 offset:1536
	ds_read_b64_tr_b16 v[22:23], v178 offset:1536
	ds_read_b64_tr_b16 v[68:69], v177 offset:1536
	ds_read_b64_tr_b16 v[70:71], v179 offset:1536
	s_waitcnt lgkmcnt(0)
	s_nop 0
	v_mfma_f32_16x16x32_bf16 v[44:47], v[16:19], v[44:47], v[84:87]
	v_mfma_f32_16x16x32_bf16 v[40:43], v[16:19], v[40:43], v[80:83]
	v_mfma_f32_16x16x32_bf16 v[36:39], v[16:19], v[36:39], v[76:79]
	v_mfma_f32_16x16x32_bf16 v[32:35], v[16:19], v[32:35], v[56:59]
	v_mfma_f32_16x16x32_bf16 v[28:31], v[16:19], v[28:31], v[52:55]
	v_mfma_f32_16x16x32_bf16 v[24:27], v[16:19], v[24:27], v[48:51]
	v_mfma_f32_16x16x32_bf16 v[20:23], v[16:19], v[20:23], v[60:63]
	v_mfma_f32_16x16x32_bf16 v[16:19], v[16:19], v[68:71], v[64:67]
	s_mov_b64 s[0:1], exec
	v_readlane_b32 s2, v253, 5
	v_readlane_b32 s3, v253, 6
	s_and_b64 s[2:3], s[0:1], s[2:3]
	s_mov_b64 exec, s[2:3]
	s_cbranch_execz .LBB0_2273
; #define LAS __attribute__((address_space(3)))
; DI unsigned f2bf(float f) { unsigned u = __builtin_bit_cast(unsigned, f); return (u + 0x7fffu + ((u >> 16) & 1u)) >> 16; }
; DI void attn_worker(unsigned char* ws, LAS unsigned char* lds, LAS unsigned* qctr, int wave) {
;     ...
;         { LAS unsigned short* ob = (LAS unsigned short*)(lds + 2048);
;           if (lane < 16) {
; #pragma unroll
;             for (int nt = 0; nt < 8; ++nt)
; #pragma unroll
;                 for (int e = 0; e < 4; ++e) ob[e * 128 + 16 * nt + lane] = f2bf(acc[nt][e]); }
	v_bfe_u32 v48, v44, 16, 1
	v_add3_u32 v44, v44, v48, s79
	ds_write_b16_d16_hi v238, v44 offset:2048
	v_bfe_u32 v44, v45, 16, 1
	v_add3_u32 v44, v45, v44, s79
	ds_write_b16_d16_hi v238, v44 offset:2304
	v_bfe_u32 v44, v46, 16, 1
	v_add3_u32 v44, v46, v44, s79
	ds_write_b16_d16_hi v238, v44 offset:2560
	v_bfe_u32 v44, v47, 16, 1
	v_add3_u32 v44, v47, v44, s79
	ds_write_b16_d16_hi v238, v44 offset:2816
	v_bfe_u32 v44, v40, 16, 1
	v_add3_u32 v40, v40, v44, s79
	ds_write_b16_d16_hi v238, v40 offset:2080
	v_bfe_u32 v40, v41, 16, 1
	v_add3_u32 v40, v41, v40, s79
	ds_write_b16_d16_hi v238, v40 offset:2336
	v_bfe_u32 v40, v42, 16, 1
	v_add3_u32 v40, v42, v40, s79
	ds_write_b16_d16_hi v238, v40 offset:2592
	v_bfe_u32 v40, v43, 16, 1
	v_add3_u32 v40, v43, v40, s79
	ds_write_b16_d16_hi v238, v40 offset:2848
	v_bfe_u32 v40, v36, 16, 1
	v_add3_u32 v36, v36, v40, s79
	ds_write_b16_d16_hi v238, v36 offset:2112
	v_bfe_u32 v36, v37, 16, 1
	v_add3_u32 v36, v37, v36, s79
	ds_write_b16_d16_hi v238, v36 offset:2368
	v_bfe_u32 v36, v38, 16, 1
	v_add3_u32 v36, v38, v36, s79
	ds_write_b16_d16_hi v238, v36 offset:2624
	v_bfe_u32 v36, v39, 16, 1
	v_add3_u32 v36, v39, v36, s79
	ds_write_b16_d16_hi v238, v36 offset:2880
	v_bfe_u32 v36, v32, 16, 1
	v_add3_u32 v32, v32, v36, s79
	ds_write_b16_d16_hi v238, v32 offset:2144
	v_bfe_u32 v32, v33, 16, 1
	v_add3_u32 v32, v33, v32, s79
	ds_write_b16_d16_hi v238, v32 offset:2400
	v_bfe_u32 v32, v34, 16, 1
	v_add3_u32 v32, v34, v32, s79
	ds_write_b16_d16_hi v238, v32 offset:2656
	v_bfe_u32 v32, v35, 16, 1
	v_add3_u32 v32, v35, v32, s79
	ds_write_b16_d16_hi v238, v32 offset:2912
	v_bfe_u32 v32, v28, 16, 1
	v_add3_u32 v28, v28, v32, s79
	ds_write_b16_d16_hi v238, v28 offset:2176
	v_bfe_u32 v28, v29, 16, 1
	v_add3_u32 v28, v29, v28, s79
	ds_write_b16_d16_hi v238, v28 offset:2432
	v_bfe_u32 v28, v30, 16, 1
	v_add3_u32 v28, v30, v28, s79
	ds_write_b16_d16_hi v238, v28 offset:2688
	v_bfe_u32 v28, v31, 16, 1
	v_add3_u32 v28, v31, v28, s79
	ds_write_b16_d16_hi v238, v28 offset:2944
	v_bfe_u32 v28, v24, 16, 1
	v_add3_u32 v24, v24, v28, s79
	ds_write_b16_d16_hi v238, v24 offset:2208
	v_bfe_u32 v24, v25, 16, 1
	v_add3_u32 v24, v25, v24, s79
	ds_write_b16_d16_hi v238, v24 offset:2464
	v_bfe_u32 v24, v26, 16, 1
	v_add3_u32 v24, v26, v24, s79
	ds_write_b16_d16_hi v238, v24 offset:2720
	v_bfe_u32 v24, v27, 16, 1
	v_add3_u32 v24, v27, v24, s79
	ds_write_b16_d16_hi v238, v24 offset:2976
	v_bfe_u32 v24, v20, 16, 1
	v_add3_u32 v20, v20, v24, s79
	ds_write_b16_d16_hi v238, v20 offset:2240
	v_bfe_u32 v20, v21, 16, 1
	v_add3_u32 v20, v21, v20, s79
	ds_write_b16_d16_hi v238, v20 offset:2496
	v_bfe_u32 v20, v22, 16, 1
	v_add3_u32 v20, v22, v20, s79
	ds_write_b16_d16_hi v238, v20 offset:2752
	v_bfe_u32 v20, v23, 16, 1
	v_add3_u32 v20, v23, v20, s79
	ds_write_b16_d16_hi v238, v20 offset:3008
	v_bfe_u32 v20, v16, 16, 1
	v_add3_u32 v16, v16, v20, s79
	ds_write_b16_d16_hi v238, v16 offset:2272
	v_bfe_u32 v16, v17, 16, 1
	v_add3_u32 v16, v17, v16, s79
	ds_write_b16_d16_hi v238, v16 offset:2528
	v_bfe_u32 v16, v18, 16, 1
	v_add3_u32 v16, v18, v16, s79
	ds_write_b16_d16_hi v238, v16 offset:2784
	v_bfe_u32 v16, v19, 16, 1
	v_add3_u32 v16, v19, v16, s79
	ds_write_b16_d16_hi v238, v16 offset:3040
	s_branch .LBB0_2273
